# K-loops: priority raise placed before the load segment's waits; priority drop issued 4 MFMAs before the closing barrier (no instruction between the last MFMA and the barrier)
# baseline (speedup 1.0000x reference)
; #define PG8_STAGE(bufoff, gbase, voff) do { _Pragma("unroll") for (int _i = 0; _i < 2; ++_i) \
;         __builtin_amdgcn_global_load_lds((const unsigned*)((const char*)(gbase) + (voff)[_i]), (PG8_LAS unsigned*)(lds + (bufoff) + ldsw + _i * 8192), 16, 0, 0); } while (0)
; #define PG8_LDA(dst, b, h) do { _Pragma("unroll") for (int m = 0; m < 4; ++m) _Pragma("unroll") for (int k = 0; k < 2; ++k) dst[m][k] = *(const PG8_LAS bf16x8*)(lds + PG8_SA(b, h) + aoff + m * 2048 + k * 1024); } while (0)
; #define PG8_LDB(dst, b, h) do { _Pragma("unroll") for (int n = 0; n < 2; ++n) _Pragma("unroll") for (int k = 0; k < 2; ++k) dst[n][k] = *(const PG8_LAS bf16x8*)(lds + PG8_SB(b, h) + boff + n * 2048 + k * 1024); } while (0)
; #define PG8_WAIT_V(n) asm volatile("s_waitcnt vmcnt(" #n ")" ::: "memory")
; #define PG8_WAIT_L(n) asm volatile("s_waitcnt lgkmcnt(" #n ")" ::: "memory")
; #define PG8_BAR __builtin_amdgcn_s_barrier()
; #define PG8_SCHED __builtin_amdgcn_sched_barrier(0)
; template <class Epi, class Sched, bool ALIGN_EPI = false, bool SP2 = false>
; __device__ __forceinline__ void gemm_phase(PG8_LAS unsigned char* lds, const Gemm g, const Sched& S, const Epi& E) {
;     ...
;         const char* nA = has_next ? (const char*)g.A + (size_t)nxt.pm * tstep : cA; const char* nB = has_next ? (const char*)g.Bt + (size_t)nxt.pn * tstep : cB;
;         for (int t = 0; t < nt; t += 2) {
;             const bool last = (t == nt - 2);
;             const char* a1 = cA + (size_t)(t + 1) * kstep;
;             const char* a2 = last ? nA : cA + (size_t)(t + 2) * kstep; const char* b2 = last ? nB : cB + (size_t)(t + 2) * kstep;
;             const char* a3 = a2 + kstep; const char* b3 = b2 + kstep;
;             if (last && has_next) S.a_ready(nxt);
;             if constexpr (SP2) {
;             PG8_LDB(B0, 0, 0); PG8_LDB(B1, 0, 1); PG8_SCHED; PG8_LDA(At, 0, 0); PG8_STAGE(PG8_SA(1, 1), a1 + hstep, voffA);
;             PG8_WAIT_V(8); PG8_WAIT_L(0); PG8_BAR; PG8_MMA(0, 0, At, B0); PG8_MMA(0, 1, At, B1); PG8_BAR; PG8_SCHED;
;             PG8_LDA(At, 0, 1); PG8_STAGE(PG8_SB(0, 0), b2, voffB); PG8_STAGE(PG8_SB(0, 1), b2 + hstep, voffB); PG8_STAGE(PG8_SA(0, 0), a2, voffA);
;             PG8_WAIT_V(8); PG8_WAIT_L(0); PG8_BAR; PG8_MMA(1, 0, At, B0); PG8_MMA(1, 1, At, B1); PG8_BAR; PG8_SCHED;
.LBB0_36:
	s_add_u32 s18, s58, 0xffe00080
	s_addc_u32 s19, s59, -1
	s_add_i32 s47, 0, 0x10000
	s_cmpk_eq_i32 s46, 0x7c
	s_cselect_b32 s63, s45, s19
	s_cselect_b32 s62, s73, s18
	v_add_u32_e32 v160, s47, v143
	s_cselect_b32 s19, s37, s79
	s_cselect_b32 s18, s84, s78
	s_add_i32 s80, 0, 0x14000
	ds_read_b128 v[156:159], v160
	ds_read_b128 v[164:167], v160 offset:1024
	ds_read_b128 v[168:171], v160 offset:2048
	ds_read_b128 v[172:175], v160 offset:3072
	v_add_u32_e32 v160, s80, v143
	ds_read_b128 v[176:179], v160
	ds_read_b128 v[180:183], v160 offset:1024
	ds_read_b128 v[184:187], v160 offset:2048
	ds_read_b128 v[204:207], v160 offset:3072
	v_lshl_add_u64 v[160:161], s[58:59], 0, v[152:153]
	s_add_i32 m0, s5, 0xc000
	ds_read_b128 v[208:211], v163
	ds_read_b128 v[212:215], v163 offset:1024
	ds_read_b128 v[216:219], v163 offset:2048
	ds_read_b128 v[220:223], v163 offset:3072
	ds_read_b128 v[224:227], v163 offset:4096
	ds_read_b128 v[228:231], v163 offset:5120
	ds_read_b128 v[232:235], v163 offset:6144
	ds_read_b128 v[236:239], v163 offset:7168
	global_load_lds_dwordx4 v[160:161], off
	v_lshl_add_u64 v[160:161], s[58:59], 0, v[154:155]
	s_add_i32 m0, s5, 0xe000
	s_nop 0
	global_load_lds_dwordx4 v[160:161], off
	s_nop 0
	s_setprio 1
	s_waitcnt vmcnt(8)
	s_waitcnt lgkmcnt(0)
	s_barrier
	v_mfma_f32_16x16x32_bf16 v[126:129], v[156:159], v[208:211], v[126:129]
	v_mfma_f32_16x16x32_bf16 v[122:125], v[168:171], v[208:211], v[122:125]
	v_mfma_f32_16x16x32_bf16 v[110:113], v[156:159], v[216:219], v[110:113]
	v_mfma_f32_16x16x32_bf16 v[106:109], v[168:171], v[216:219], v[106:109]
	v_mfma_f32_16x16x32_bf16 v[94:97], v[156:159], v[224:227], v[94:97]
	v_mfma_f32_16x16x32_bf16 v[90:93], v[168:171], v[224:227], v[90:93]
	v_mfma_f32_16x16x32_bf16 v[78:81], v[156:159], v[232:235], v[78:81]
	v_mfma_f32_16x16x32_bf16 v[74:77], v[168:171], v[232:235], v[74:77]
	s_setprio 0
	s_setprio 1
	v_mfma_f32_16x16x32_bf16 v[126:129], v[164:167], v[212:215], v[126:129]
	v_mfma_f32_16x16x32_bf16 v[122:125], v[172:175], v[212:215], v[122:125]
	v_mfma_f32_16x16x32_bf16 v[110:113], v[164:167], v[220:223], v[110:113]
	v_mfma_f32_16x16x32_bf16 v[106:109], v[172:175], v[220:223], v[106:109]
	v_mfma_f32_16x16x32_bf16 v[94:97], v[164:167], v[228:231], v[94:97]
	v_mfma_f32_16x16x32_bf16 v[90:93], v[172:175], v[228:231], v[90:93]
	v_mfma_f32_16x16x32_bf16 v[78:81], v[164:167], v[236:239], v[78:81]
	v_mfma_f32_16x16x32_bf16 v[74:77], v[172:175], v[236:239], v[74:77]
	s_setprio 0
	s_setprio 1
	v_mfma_f32_16x16x32_bf16 v[118:121], v[176:179], v[208:211], v[118:121]
	v_mfma_f32_16x16x32_bf16 v[114:117], v[184:187], v[208:211], v[114:117]
	v_mfma_f32_16x16x32_bf16 v[102:105], v[176:179], v[216:219], v[102:105]
	v_mfma_f32_16x16x32_bf16 v[98:101], v[184:187], v[216:219], v[98:101]
	v_mfma_f32_16x16x32_bf16 v[86:89], v[176:179], v[224:227], v[86:89]
	v_mfma_f32_16x16x32_bf16 v[82:85], v[184:187], v[224:227], v[82:85]
	v_mfma_f32_16x16x32_bf16 v[70:73], v[176:179], v[232:235], v[70:73]
	v_mfma_f32_16x16x32_bf16 v[66:69], v[184:187], v[232:235], v[66:69]
	s_setprio 0
	s_setprio 1
	v_mfma_f32_16x16x32_bf16 v[118:121], v[180:183], v[212:215], v[118:121]
	v_mfma_f32_16x16x32_bf16 v[114:117], v[204:207], v[212:215], v[114:117]
	v_mfma_f32_16x16x32_bf16 v[102:105], v[180:183], v[220:223], v[102:105]
	v_mfma_f32_16x16x32_bf16 v[98:101], v[204:207], v[220:223], v[98:101]
	s_setprio 0
	v_mfma_f32_16x16x32_bf16 v[86:89], v[180:183], v[228:231], v[86:89]
	v_mfma_f32_16x16x32_bf16 v[82:85], v[204:207], v[228:231], v[82:85]
	v_mfma_f32_16x16x32_bf16 v[70:73], v[180:183], v[236:239], v[70:73]
	v_mfma_f32_16x16x32_bf16 v[66:69], v[204:207], v[236:239], v[66:69]
	s_barrier
	s_add_i32 s47, s47, s4
	v_lshl_add_u64 v[160:161], s[18:19], 0, v[148:149]
	s_mov_b32 m0, s47
	ds_read_b128 v[208:211], v163 offset:16384
	ds_read_b128 v[212:215], v163 offset:17408
	ds_read_b128 v[216:219], v163 offset:18432
	ds_read_b128 v[220:223], v163 offset:19456
	ds_read_b128 v[224:227], v163 offset:20480
	ds_read_b128 v[228:231], v163 offset:21504
	ds_read_b128 v[232:235], v163 offset:22528
	ds_read_b128 v[236:239], v163 offset:23552
	global_load_lds_dwordx4 v[160:161], off
	s_add_i32 m0, s47, 0x2000
	s_add_u32 s76, s18, 0x200000
	v_lshl_add_u64 v[240:241], s[18:19], 0, v[144:145]
	s_addc_u32 s77, s19, 0
	s_add_i32 s47, s80, s4
	global_load_lds_dwordx4 v[240:241], off
	v_lshl_add_u64 v[242:243], s[76:77], 0, v[148:149]
	s_mov_b32 m0, s47
	v_lshl_add_u64 v[244:245], s[62:63], 0, v[146:147]
	global_load_lds_dwordx4 v[242:243], off
	v_lshl_add_u64 v[242:243], s[76:77], 0, v[144:145]
	s_add_i32 m0, s47, 0x2000
	s_nop 0
	global_load_lds_dwordx4 v[242:243], off
	v_lshl_add_u64 v[242:243], s[62:63], 0, v[150:151]
	s_mov_b32 m0, s5
	s_nop 0
	global_load_lds_dwordx4 v[242:243], off
	s_mov_b32 m0, s30
	s_nop 0
	global_load_lds_dwordx4 v[244:245], off
	s_setprio 1
	s_waitcnt vmcnt(8)
	s_waitcnt lgkmcnt(0)
	s_barrier
; #define PG8_STAGE(bufoff, gbase, voff) do { _Pragma("unroll") for (int _i = 0; _i < 2; ++_i) \
;         __builtin_amdgcn_global_load_lds((const unsigned*)((const char*)(gbase) + (voff)[_i]), (PG8_LAS unsigned*)(lds + (bufoff) + ldsw + _i * 8192), 16, 0, 0); } while (0)
; #define PG8_LDA(dst, b, h) do { _Pragma("unroll") for (int m = 0; m < 4; ++m) _Pragma("unroll") for (int k = 0; k < 2; ++k) dst[m][k] = *(const PG8_LAS bf16x8*)(lds + PG8_SA(b, h) + aoff + m * 2048 + k * 1024); } while (0)
; #define PG8_LDB(dst, b, h) do { _Pragma("unroll") for (int n = 0; n < 2; ++n) _Pragma("unroll") for (int k = 0; k < 2; ++k) dst[n][k] = *(const PG8_LAS bf16x8*)(lds + PG8_SB(b, h) + boff + n * 2048 + k * 1024); } while (0)
; #define PG8_MMA(ai, bj, At, Bt) do { __builtin_amdgcn_s_setprio(1); _Pragma("unroll") for (int m = 0; m < 4; ++m) _Pragma("unroll") for (int n = 0; n < 2; ++n) _Pragma("unroll") for (int k = 0; k < 2; ++k) \
;         acc[ai][bj][m][n] = __builtin_amdgcn_mfma_f32_16x16x32_bf16(Bt[n][k], At[m][k], acc[ai][bj][m][n], 0, 0, 0); __builtin_amdgcn_s_setprio(0); } while (0)
; #define PG8_WAIT_V(n) asm volatile("s_waitcnt vmcnt(" #n ")" ::: "memory")
; #define PG8_WAIT_L(n) asm volatile("s_waitcnt lgkmcnt(" #n ")" ::: "memory")
; #define PG8_BAR __builtin_amdgcn_s_barrier()
; #define PG8_SCHED __builtin_amdgcn_sched_barrier(0)
; template <class Epi, class Sched, bool ALIGN_EPI = false, bool SP2 = false>
; __device__ __forceinline__ void gemm_phase(PG8_LAS unsigned char* lds, const Gemm g, const Sched& S, const Epi& E) {
;     ...
;             PG8_WAIT_V(8); PG8_WAIT_L(0); PG8_BAR; PG8_MMA(1, 0, At, B0); PG8_MMA(1, 1, At, B1); PG8_BAR; PG8_SCHED;
;             PG8_LDB(B0, 1, 0); PG8_LDB(B1, 1, 1); PG8_SCHED; PG8_LDA(At, 1, 0); PG8_STAGE(PG8_SA(0, 1), a2 + hstep, voffA);
;             PG8_WAIT_V(8); PG8_WAIT_L(0); PG8_BAR; PG8_MMA(0, 0, At, B0); PG8_MMA(0, 1, At, B1); PG8_BAR; PG8_SCHED;
	v_mfma_f32_16x16x32_bf16 v[62:65], v[156:159], v[208:211], v[62:65]
	v_mfma_f32_16x16x32_bf16 v[58:61], v[168:171], v[208:211], v[58:61]
	v_mfma_f32_16x16x32_bf16 v[46:49], v[156:159], v[216:219], v[46:49]
	v_mfma_f32_16x16x32_bf16 v[42:45], v[168:171], v[216:219], v[42:45]
	v_mfma_f32_16x16x32_bf16 v[30:33], v[156:159], v[224:227], v[30:33]
	v_mfma_f32_16x16x32_bf16 v[26:29], v[168:171], v[224:227], v[26:29]
	v_mfma_f32_16x16x32_bf16 v[14:17], v[156:159], v[232:235], v[14:17]
	v_mfma_f32_16x16x32_bf16 v[10:13], v[168:171], v[232:235], v[10:13]
	s_setprio 0
	s_setprio 1
	v_mfma_f32_16x16x32_bf16 v[62:65], v[164:167], v[212:215], v[62:65]
	v_mfma_f32_16x16x32_bf16 v[58:61], v[172:175], v[212:215], v[58:61]
	v_mfma_f32_16x16x32_bf16 v[46:49], v[164:167], v[220:223], v[46:49]
	v_mfma_f32_16x16x32_bf16 v[42:45], v[172:175], v[220:223], v[42:45]
	v_mfma_f32_16x16x32_bf16 v[30:33], v[164:167], v[228:231], v[30:33]
	v_mfma_f32_16x16x32_bf16 v[26:29], v[172:175], v[228:231], v[26:29]
	v_mfma_f32_16x16x32_bf16 v[14:17], v[164:167], v[236:239], v[14:17]
	v_mfma_f32_16x16x32_bf16 v[10:13], v[172:175], v[236:239], v[10:13]
	s_setprio 0
	s_setprio 1
	v_mfma_f32_16x16x32_bf16 v[54:57], v[176:179], v[208:211], v[54:57]
	v_mfma_f32_16x16x32_bf16 v[50:53], v[184:187], v[208:211], v[50:53]
	v_mfma_f32_16x16x32_bf16 v[38:41], v[176:179], v[216:219], v[38:41]
	v_mfma_f32_16x16x32_bf16 v[34:37], v[184:187], v[216:219], v[34:37]
	v_mfma_f32_16x16x32_bf16 v[22:25], v[176:179], v[224:227], v[22:25]
	v_mfma_f32_16x16x32_bf16 v[18:21], v[184:187], v[224:227], v[18:21]
	v_mfma_f32_16x16x32_bf16 v[6:9], v[176:179], v[232:235], v[6:9]
	v_mfma_f32_16x16x32_bf16 v[2:5], v[184:187], v[232:235], v[2:5]
	s_setprio 0
	s_setprio 1
	v_mfma_f32_16x16x32_bf16 v[54:57], v[180:183], v[212:215], v[54:57]
	v_mfma_f32_16x16x32_bf16 v[50:53], v[204:207], v[212:215], v[50:53]
	v_mfma_f32_16x16x32_bf16 v[38:41], v[180:183], v[220:223], v[38:41]
	v_mfma_f32_16x16x32_bf16 v[34:37], v[204:207], v[220:223], v[34:37]
	s_setprio 0
	v_mfma_f32_16x16x32_bf16 v[22:25], v[180:183], v[228:231], v[22:25]
	v_mfma_f32_16x16x32_bf16 v[18:21], v[204:207], v[228:231], v[18:21]
	v_mfma_f32_16x16x32_bf16 v[6:9], v[180:183], v[236:239], v[6:9]
	v_mfma_f32_16x16x32_bf16 v[2:5], v[204:207], v[236:239], v[2:5]
	s_barrier
	s_add_i32 s47, 0, 0x18000
	s_add_i32 s76, 0, 0x1c000
	v_add_u32_e32 v172, s47, v143
	v_add_u32_e32 v203, s76, v143
	ds_read_b128 v[156:159], v172
	ds_read_b128 v[164:167], v172 offset:1024
	ds_read_b128 v[168:171], v172 offset:2048
	ds_read_b128 v[172:175], v172 offset:3072
	ds_read_b128 v[176:179], v203
	ds_read_b128 v[180:183], v203 offset:1024
	ds_read_b128 v[184:187], v203 offset:2048
	ds_read_b128 v[204:207], v203 offset:3072
	s_add_u32 s62, s62, 0x200000
	s_addc_u32 s63, s63, 0
	s_mov_b32 m0, s57
	v_lshl_add_u64 v[246:247], s[62:63], 0, v[150:151]
	ds_read_b128 v[208:211], v163 offset:32768
	ds_read_b128 v[212:215], v163 offset:33792
	ds_read_b128 v[216:219], v163 offset:34816
	ds_read_b128 v[220:223], v163 offset:35840
	ds_read_b128 v[224:227], v163 offset:36864
	ds_read_b128 v[228:231], v163 offset:37888
	ds_read_b128 v[232:235], v163 offset:38912
	ds_read_b128 v[236:239], v163 offset:39936
	global_load_lds_dwordx4 v[246:247], off
	v_lshl_add_u64 v[246:247], s[62:63], 0, v[146:147]
	s_mov_b32 m0, s67
	s_nop 0
	global_load_lds_dwordx4 v[246:247], off
	s_setprio 1
	s_waitcnt vmcnt(8)
	s_waitcnt lgkmcnt(0)
	s_barrier
	v_mfma_f32_16x16x32_bf16 v[126:129], v[156:159], v[208:211], v[126:129]
	v_mfma_f32_16x16x32_bf16 v[122:125], v[168:171], v[208:211], v[122:125]
	v_mfma_f32_16x16x32_bf16 v[110:113], v[156:159], v[216:219], v[110:113]
	v_mfma_f32_16x16x32_bf16 v[106:109], v[168:171], v[216:219], v[106:109]
	v_mfma_f32_16x16x32_bf16 v[94:97], v[156:159], v[224:227], v[94:97]
	v_mfma_f32_16x16x32_bf16 v[90:93], v[168:171], v[224:227], v[90:93]
	v_mfma_f32_16x16x32_bf16 v[78:81], v[156:159], v[232:235], v[78:81]
	v_mfma_f32_16x16x32_bf16 v[74:77], v[168:171], v[232:235], v[74:77]
	s_setprio 0
	s_setprio 1
	v_mfma_f32_16x16x32_bf16 v[126:129], v[164:167], v[212:215], v[126:129]
	v_mfma_f32_16x16x32_bf16 v[122:125], v[172:175], v[212:215], v[122:125]
	v_mfma_f32_16x16x32_bf16 v[110:113], v[164:167], v[220:223], v[110:113]
	v_mfma_f32_16x16x32_bf16 v[106:109], v[172:175], v[220:223], v[106:109]
	v_mfma_f32_16x16x32_bf16 v[94:97], v[164:167], v[228:231], v[94:97]
	v_mfma_f32_16x16x32_bf16 v[90:93], v[172:175], v[228:231], v[90:93]
	v_mfma_f32_16x16x32_bf16 v[78:81], v[164:167], v[236:239], v[78:81]
	v_mfma_f32_16x16x32_bf16 v[74:77], v[172:175], v[236:239], v[74:77]
	s_setprio 0
	s_setprio 1
	v_mfma_f32_16x16x32_bf16 v[118:121], v[176:179], v[208:211], v[118:121]
	v_mfma_f32_16x16x32_bf16 v[114:117], v[184:187], v[208:211], v[114:117]
	v_mfma_f32_16x16x32_bf16 v[102:105], v[176:179], v[216:219], v[102:105]
	v_mfma_f32_16x16x32_bf16 v[98:101], v[184:187], v[216:219], v[98:101]
	v_mfma_f32_16x16x32_bf16 v[86:89], v[176:179], v[224:227], v[86:89]
	v_mfma_f32_16x16x32_bf16 v[82:85], v[184:187], v[224:227], v[82:85]
	v_mfma_f32_16x16x32_bf16 v[70:73], v[176:179], v[232:235], v[70:73]
	v_mfma_f32_16x16x32_bf16 v[66:69], v[184:187], v[232:235], v[66:69]
	s_setprio 0
	s_setprio 1
	v_mfma_f32_16x16x32_bf16 v[118:121], v[180:183], v[212:215], v[118:121]
	v_mfma_f32_16x16x32_bf16 v[114:117], v[204:207], v[212:215], v[114:117]
	v_mfma_f32_16x16x32_bf16 v[102:105], v[180:183], v[220:223], v[102:105]
	v_mfma_f32_16x16x32_bf16 v[98:101], v[204:207], v[220:223], v[98:101]
	s_setprio 0
	v_mfma_f32_16x16x32_bf16 v[86:89], v[180:183], v[228:231], v[86:89]
	v_mfma_f32_16x16x32_bf16 v[82:85], v[204:207], v[228:231], v[82:85]
	v_mfma_f32_16x16x32_bf16 v[70:73], v[180:183], v[236:239], v[70:73]
	v_mfma_f32_16x16x32_bf16 v[66:69], v[204:207], v[236:239], v[66:69]
	s_barrier
; #define PG8_STAGE(bufoff, gbase, voff) do { _Pragma("unroll") for (int _i = 0; _i < 2; ++_i) \
;         __builtin_amdgcn_global_load_lds((const unsigned*)((const char*)(gbase) + (voff)[_i]), (PG8_LAS unsigned*)(lds + (bufoff) + ldsw + _i * 8192), 16, 0, 0); } while (0)
; #define PG8_LDA(dst, b, h) do { _Pragma("unroll") for (int m = 0; m < 4; ++m) _Pragma("unroll") for (int k = 0; k < 2; ++k) dst[m][k] = *(const PG8_LAS bf16x8*)(lds + PG8_SA(b, h) + aoff + m * 2048 + k * 1024); } while (0)
; #define PG8_MMA(ai, bj, At, Bt) do { __builtin_amdgcn_s_setprio(1); _Pragma("unroll") for (int m = 0; m < 4; ++m) _Pragma("unroll") for (int n = 0; n < 2; ++n) _Pragma("unroll") for (int k = 0; k < 2; ++k) \
;         acc[ai][bj][m][n] = __builtin_amdgcn_mfma_f32_16x16x32_bf16(Bt[n][k], At[m][k], acc[ai][bj][m][n], 0, 0, 0); __builtin_amdgcn_s_setprio(0); } while (0)
; #define PG8_WAIT_V(n) asm volatile("s_waitcnt vmcnt(" #n ")" ::: "memory")
; #define PG8_WAIT_L(n) asm volatile("s_waitcnt lgkmcnt(" #n ")" ::: "memory")
; #define PG8_BAR __builtin_amdgcn_s_barrier()
; #define PG8_SCHED __builtin_amdgcn_sched_barrier(0)
; template <class Epi, class Sched, bool ALIGN_EPI = false, bool SP2 = false>
; __device__ __forceinline__ void gemm_phase(PG8_LAS unsigned char* lds, const Gemm g, const Sched& S, const Epi& E) {
;     ...
;             PG8_LDA(At, 1, 1); PG8_STAGE(PG8_SB(1, 0), b3, voffB); PG8_STAGE(PG8_SB(1, 1), b3 + hstep, voffB); PG8_STAGE(PG8_SA(1, 0), a3, voffA);
;             PG8_WAIT_V(8); PG8_WAIT_L(0); PG8_BAR; PG8_MMA(1, 0, At, B0); PG8_MMA(1, 1, At, B1); PG8_BAR; PG8_SCHED;
;     ...
;         if constexpr (ALIGN_EPI) { if (wr == 0) PG8_BAR; }
	s_add_i32 s47, s47, s4
	v_lshl_add_u64 v[160:161], v[160:161], 0, s[68:69]
	s_mov_b32 m0, s47
	ds_read_b128 v[208:211], v163 offset:49152
	ds_read_b128 v[212:215], v163 offset:50176
	ds_read_b128 v[216:219], v163 offset:51200
	ds_read_b128 v[220:223], v163 offset:52224
	ds_read_b128 v[224:227], v163 offset:53248
	ds_read_b128 v[228:231], v163 offset:54272
	ds_read_b128 v[232:235], v163 offset:55296
	ds_read_b128 v[236:239], v163 offset:56320
	global_load_lds_dwordx4 v[160:161], off
	s_add_i32 m0, s47, 0x2000
	s_add_u32 s18, s18, 0x200080
	v_lshl_add_u64 v[160:161], v[240:241], 0, s[68:69]
	s_addc_u32 s19, s19, 0
	s_add_i32 s47, s76, s4
	global_load_lds_dwordx4 v[160:161], off
	v_lshl_add_u64 v[160:161], s[18:19], 0, v[148:149]
	s_mov_b32 m0, s47
	s_nop 0
	global_load_lds_dwordx4 v[160:161], off
	v_lshl_add_u64 v[160:161], s[18:19], 0, v[144:145]
	s_add_i32 m0, s47, 0x2000
	s_nop 0
	global_load_lds_dwordx4 v[160:161], off
	v_lshl_add_u64 v[160:161], v[242:243], 0, s[68:69]
	s_mov_b32 m0, s1
	s_nop 0
	global_load_lds_dwordx4 v[160:161], off
	v_lshl_add_u64 v[160:161], v[244:245], 0, s[68:69]
	s_mov_b32 m0, s60
	s_nop 0
	global_load_lds_dwordx4 v[160:161], off
	s_nop 0
	s_setprio 1
	s_waitcnt vmcnt(8)
	s_waitcnt lgkmcnt(0)
	s_barrier
	v_mfma_f32_16x16x32_bf16 v[62:65], v[156:159], v[208:211], v[62:65]
	v_mfma_f32_16x16x32_bf16 v[58:61], v[168:171], v[208:211], v[58:61]
	v_mfma_f32_16x16x32_bf16 v[46:49], v[156:159], v[216:219], v[46:49]
	v_mfma_f32_16x16x32_bf16 v[42:45], v[168:171], v[216:219], v[42:45]
	v_mfma_f32_16x16x32_bf16 v[30:33], v[156:159], v[224:227], v[30:33]
	v_mfma_f32_16x16x32_bf16 v[26:29], v[168:171], v[224:227], v[26:29]
	v_mfma_f32_16x16x32_bf16 v[14:17], v[156:159], v[232:235], v[14:17]
	v_mfma_f32_16x16x32_bf16 v[10:13], v[168:171], v[232:235], v[10:13]
	s_setprio 0
	s_setprio 1
	v_mfma_f32_16x16x32_bf16 v[62:65], v[164:167], v[212:215], v[62:65]
	v_mfma_f32_16x16x32_bf16 v[58:61], v[172:175], v[212:215], v[58:61]
	v_mfma_f32_16x16x32_bf16 v[46:49], v[164:167], v[220:223], v[46:49]
	v_mfma_f32_16x16x32_bf16 v[42:45], v[172:175], v[220:223], v[42:45]
	v_mfma_f32_16x16x32_bf16 v[30:33], v[164:167], v[228:231], v[30:33]
	v_mfma_f32_16x16x32_bf16 v[26:29], v[172:175], v[228:231], v[26:29]
	v_mfma_f32_16x16x32_bf16 v[14:17], v[164:167], v[236:239], v[14:17]
	v_mfma_f32_16x16x32_bf16 v[10:13], v[172:175], v[236:239], v[10:13]
	s_setprio 0
	s_setprio 1
	v_mfma_f32_16x16x32_bf16 v[54:57], v[176:179], v[208:211], v[54:57]
	v_mfma_f32_16x16x32_bf16 v[50:53], v[184:187], v[208:211], v[50:53]
	v_mfma_f32_16x16x32_bf16 v[38:41], v[176:179], v[216:219], v[38:41]
	v_mfma_f32_16x16x32_bf16 v[34:37], v[184:187], v[216:219], v[34:37]
	v_mfma_f32_16x16x32_bf16 v[22:25], v[176:179], v[224:227], v[22:25]
	v_mfma_f32_16x16x32_bf16 v[18:21], v[184:187], v[224:227], v[18:21]
	v_mfma_f32_16x16x32_bf16 v[6:9], v[176:179], v[232:235], v[6:9]
	v_mfma_f32_16x16x32_bf16 v[2:5], v[184:187], v[232:235], v[2:5]
	s_setprio 0
	s_setprio 1
	v_mfma_f32_16x16x32_bf16 v[54:57], v[180:183], v[212:215], v[54:57]
	v_mfma_f32_16x16x32_bf16 v[50:53], v[204:207], v[212:215], v[50:53]
	v_mfma_f32_16x16x32_bf16 v[38:41], v[180:183], v[220:223], v[38:41]
	v_mfma_f32_16x16x32_bf16 v[34:37], v[204:207], v[220:223], v[34:37]
	s_setprio 0
	v_mfma_f32_16x16x32_bf16 v[22:25], v[180:183], v[228:231], v[22:25]
	v_mfma_f32_16x16x32_bf16 v[18:21], v[204:207], v[228:231], v[18:21]
	v_mfma_f32_16x16x32_bf16 v[6:9], v[180:183], v[236:239], v[6:9]
	v_mfma_f32_16x16x32_bf16 v[2:5], v[204:207], v[236:239], v[2:5]
	s_barrier
	s_add_i32 s46, s46, 2
	s_add_u32 s58, s58, 0x100
	s_addc_u32 s59, s59, 0
	s_add_u32 s78, s78, 0x100
	s_addc_u32 s79, s79, 0
	s_cmpk_gt_u32 s46, 0x7d
	s_cbranch_scc0 .LBB0_36
	s_and_b64 vcc, exec, s[12:13]
	s_cbranch_vccz .LBB0_39
	s_barrier

; #define PG8_STAGE(bufoff, gbase, voff) do { _Pragma("unroll") for (int _i = 0; _i < 2; ++_i) \
;         __builtin_amdgcn_global_load_lds((const unsigned*)((const char*)(gbase) + (voff)[_i]), (PG8_LAS unsigned*)(lds + (bufoff) + ldsw + _i * 8192), 16, 0, 0); } while (0)
; #define PG8_LDA(dst, b, h) do { _Pragma("unroll") for (int m = 0; m < 4; ++m) _Pragma("unroll") for (int k = 0; k < 2; ++k) dst[m][k] = *(const PG8_LAS bf16x8*)(lds + PG8_SA(b, h) + aoff + m * 2048 + k * 1024); } while (0)
; #define PG8_LDB(dst, b, h) do { _Pragma("unroll") for (int n = 0; n < 2; ++n) _Pragma("unroll") for (int k = 0; k < 2; ++k) dst[n][k] = *(const PG8_LAS bf16x8*)(lds + PG8_SB(b, h) + boff + n * 2048 + k * 1024); } while (0)
; #define PG8_WAIT_V(n) asm volatile("s_waitcnt vmcnt(" #n ")" ::: "memory")
; #define PG8_WAIT_L(n) asm volatile("s_waitcnt lgkmcnt(" #n ")" ::: "memory")
; #define PG8_BAR __builtin_amdgcn_s_barrier()
; #define PG8_SCHED __builtin_amdgcn_sched_barrier(0)
; template <class Epi, class Sched, bool ALIGN_EPI = false, bool SP2 = false>
; __device__ __forceinline__ void gemm_phase(PG8_LAS unsigned char* lds, const Gemm g, const Sched& S, const Epi& E) {
;     ...
;         const char* nA = has_next ? (const char*)g.A + (size_t)nxt.pm * tstep : cA; const char* nB = has_next ? (const char*)g.Bt + (size_t)nxt.pn * tstep : cB;
;         for (int t = 0; t < nt; t += 2) {
;             const bool last = (t == nt - 2);
;             const char* a1 = cA + (size_t)(t + 1) * kstep;
;             const char* a2 = last ? nA : cA + (size_t)(t + 2) * kstep; const char* b2 = last ? nB : cB + (size_t)(t + 2) * kstep;
;             const char* a3 = a2 + kstep; const char* b3 = b2 + kstep;
;             if (last && has_next) S.a_ready(nxt);
;             if constexpr (SP2) {
;             PG8_LDB(B0, 0, 0); PG8_LDB(B1, 0, 1); PG8_SCHED; PG8_LDA(At, 0, 0); PG8_STAGE(PG8_SA(1, 1), a1 + hstep, voffA);
;             PG8_WAIT_V(8); PG8_WAIT_L(0); PG8_BAR; PG8_MMA(0, 0, At, B0); PG8_MMA(0, 1, At, B1); PG8_BAR; PG8_SCHED;
;             PG8_LDA(At, 0, 1); PG8_STAGE(PG8_SB(0, 0), b2, voffB); PG8_STAGE(PG8_SB(0, 1), b2 + hstep, voffB); PG8_STAGE(PG8_SA(0, 0), a2, voffA);
;             PG8_WAIT_V(8); PG8_WAIT_L(0); PG8_BAR; PG8_MMA(1, 0, At, B0); PG8_MMA(1, 1, At, B1); PG8_BAR; PG8_SCHED;
.LBB0_76:
	s_add_u32 s18, s0, 0xfff80080
	s_addc_u32 s19, s1, -1
	s_add_i32 s47, 0, 0x10000
	s_cmp_eq_u32 s46, 28
	s_cselect_b32 s59, s60, s19
	s_cselect_b32 s58, s73, s18
	v_add_u32_e32 v158, s47, v143
	s_cselect_b32 s19, s45, s79
	s_cselect_b32 s18, s84, s78
	s_add_i32 s80, 0, 0x14000
	ds_read_b128 v[162:165], v158
	ds_read_b128 v[166:169], v158 offset:1024
	ds_read_b128 v[170:173], v158 offset:2048
	ds_read_b128 v[174:177], v158 offset:3072
	v_add_u32_e32 v158, s80, v143
	ds_read_b128 v[178:181], v158
	ds_read_b128 v[182:185], v158 offset:1024
	ds_read_b128 v[204:207], v158 offset:2048
	ds_read_b128 v[208:211], v158 offset:3072
	v_lshl_add_u64 v[158:159], s[0:1], 0, v[154:155]
	s_add_i32 m0, s62, 0xc000
	ds_read_b128 v[212:215], v161
	ds_read_b128 v[216:219], v161 offset:1024
	ds_read_b128 v[220:223], v161 offset:2048
	ds_read_b128 v[224:227], v161 offset:3072
	ds_read_b128 v[228:231], v161 offset:4096
	ds_read_b128 v[232:235], v161 offset:5120
	ds_read_b128 v[236:239], v161 offset:6144
	ds_read_b128 v[240:243], v161 offset:7168
	global_load_lds_dwordx4 v[158:159], off
	v_lshl_add_u64 v[158:159], s[0:1], 0, v[156:157]
	s_add_i32 m0, s62, 0xe000
	s_nop 0
	global_load_lds_dwordx4 v[158:159], off
	s_nop 0
	s_setprio 1
	s_waitcnt vmcnt(8)
	s_waitcnt lgkmcnt(0)
	s_barrier
	v_mfma_f32_16x16x32_bf16 v[126:129], v[162:165], v[212:215], v[126:129]
	v_mfma_f32_16x16x32_bf16 v[122:125], v[170:173], v[212:215], v[122:125]
	v_mfma_f32_16x16x32_bf16 v[110:113], v[162:165], v[220:223], v[110:113]
	v_mfma_f32_16x16x32_bf16 v[106:109], v[170:173], v[220:223], v[106:109]
	v_mfma_f32_16x16x32_bf16 v[94:97], v[162:165], v[228:231], v[94:97]
	v_mfma_f32_16x16x32_bf16 v[90:93], v[170:173], v[228:231], v[90:93]
	v_mfma_f32_16x16x32_bf16 v[78:81], v[162:165], v[236:239], v[78:81]
	v_mfma_f32_16x16x32_bf16 v[74:77], v[170:173], v[236:239], v[74:77]
	s_setprio 0
	s_setprio 1
	v_mfma_f32_16x16x32_bf16 v[126:129], v[166:169], v[216:219], v[126:129]
	v_mfma_f32_16x16x32_bf16 v[122:125], v[174:177], v[216:219], v[122:125]
	v_mfma_f32_16x16x32_bf16 v[110:113], v[166:169], v[224:227], v[110:113]
	v_mfma_f32_16x16x32_bf16 v[106:109], v[174:177], v[224:227], v[106:109]
	v_mfma_f32_16x16x32_bf16 v[94:97], v[166:169], v[232:235], v[94:97]
	v_mfma_f32_16x16x32_bf16 v[90:93], v[174:177], v[232:235], v[90:93]
	v_mfma_f32_16x16x32_bf16 v[78:81], v[166:169], v[240:243], v[78:81]
	v_mfma_f32_16x16x32_bf16 v[74:77], v[174:177], v[240:243], v[74:77]
	s_setprio 0
	s_setprio 1
	v_mfma_f32_16x16x32_bf16 v[118:121], v[178:181], v[212:215], v[118:121]
	v_mfma_f32_16x16x32_bf16 v[114:117], v[204:207], v[212:215], v[114:117]
	v_mfma_f32_16x16x32_bf16 v[102:105], v[178:181], v[220:223], v[102:105]
	v_mfma_f32_16x16x32_bf16 v[98:101], v[204:207], v[220:223], v[98:101]
	v_mfma_f32_16x16x32_bf16 v[86:89], v[178:181], v[228:231], v[86:89]
	v_mfma_f32_16x16x32_bf16 v[82:85], v[204:207], v[228:231], v[82:85]
	v_mfma_f32_16x16x32_bf16 v[70:73], v[178:181], v[236:239], v[70:73]
	v_mfma_f32_16x16x32_bf16 v[66:69], v[204:207], v[236:239], v[66:69]
	s_setprio 0
	s_setprio 1
	v_mfma_f32_16x16x32_bf16 v[118:121], v[182:185], v[216:219], v[118:121]
	v_mfma_f32_16x16x32_bf16 v[114:117], v[208:211], v[216:219], v[114:117]
	v_mfma_f32_16x16x32_bf16 v[102:105], v[182:185], v[224:227], v[102:105]
	v_mfma_f32_16x16x32_bf16 v[98:101], v[208:211], v[224:227], v[98:101]
	s_setprio 0
	v_mfma_f32_16x16x32_bf16 v[86:89], v[182:185], v[232:235], v[86:89]
	v_mfma_f32_16x16x32_bf16 v[82:85], v[208:211], v[232:235], v[82:85]
	v_mfma_f32_16x16x32_bf16 v[70:73], v[182:185], v[240:243], v[70:73]
	v_mfma_f32_16x16x32_bf16 v[66:69], v[208:211], v[240:243], v[66:69]
	s_barrier
	s_add_i32 s47, s47, s54
	v_lshl_add_u64 v[158:159], s[18:19], 0, v[148:149]
	s_mov_b32 m0, s47
	ds_read_b128 v[212:215], v161 offset:16384
	ds_read_b128 v[216:219], v161 offset:17408
	ds_read_b128 v[220:223], v161 offset:18432
	ds_read_b128 v[224:227], v161 offset:19456
	ds_read_b128 v[228:231], v161 offset:20480
	ds_read_b128 v[232:235], v161 offset:21504
	ds_read_b128 v[236:239], v161 offset:22528
	ds_read_b128 v[240:243], v161 offset:23552
	global_load_lds_dwordx4 v[158:159], off
	s_add_i32 m0, s47, 0x2000
	s_add_u32 s76, s18, 0x80000
	v_lshl_add_u64 v[186:187], s[18:19], 0, v[144:145]
	s_addc_u32 s77, s19, 0
	s_add_i32 s47, s80, s54
	global_load_lds_dwordx4 v[186:187], off
	v_lshl_add_u64 v[244:245], s[76:77], 0, v[148:149]
	s_mov_b32 m0, s47
	v_lshl_add_u64 v[246:247], s[58:59], 0, v[146:147]
	global_load_lds_dwordx4 v[244:245], off
	v_lshl_add_u64 v[244:245], s[76:77], 0, v[144:145]
	s_add_i32 m0, s47, 0x2000
	s_nop 0
	global_load_lds_dwordx4 v[244:245], off
	v_lshl_add_u64 v[244:245], s[58:59], 0, v[150:151]
	s_mov_b32 m0, s62
	s_nop 0
	global_load_lds_dwordx4 v[244:245], off
	s_mov_b32 m0, s63
	s_nop 0
	global_load_lds_dwordx4 v[246:247], off
	s_setprio 1
	s_waitcnt vmcnt(8)
	s_waitcnt lgkmcnt(0)
	s_barrier
; #define PG8_STAGE(bufoff, gbase, voff) do { _Pragma("unroll") for (int _i = 0; _i < 2; ++_i) \
;         __builtin_amdgcn_global_load_lds((const unsigned*)((const char*)(gbase) + (voff)[_i]), (PG8_LAS unsigned*)(lds + (bufoff) + ldsw + _i * 8192), 16, 0, 0); } while (0)
; #define PG8_LDA(dst, b, h) do { _Pragma("unroll") for (int m = 0; m < 4; ++m) _Pragma("unroll") for (int k = 0; k < 2; ++k) dst[m][k] = *(const PG8_LAS bf16x8*)(lds + PG8_SA(b, h) + aoff + m * 2048 + k * 1024); } while (0)
; #define PG8_LDB(dst, b, h) do { _Pragma("unroll") for (int n = 0; n < 2; ++n) _Pragma("unroll") for (int k = 0; k < 2; ++k) dst[n][k] = *(const PG8_LAS bf16x8*)(lds + PG8_SB(b, h) + boff + n * 2048 + k * 1024); } while (0)
; #define PG8_MMA(ai, bj, At, Bt) do { __builtin_amdgcn_s_setprio(1); _Pragma("unroll") for (int m = 0; m < 4; ++m) _Pragma("unroll") for (int n = 0; n < 2; ++n) _Pragma("unroll") for (int k = 0; k < 2; ++k) \
;         acc[ai][bj][m][n] = __builtin_amdgcn_mfma_f32_16x16x32_bf16(Bt[n][k], At[m][k], acc[ai][bj][m][n], 0, 0, 0); __builtin_amdgcn_s_setprio(0); } while (0)
; #define PG8_WAIT_V(n) asm volatile("s_waitcnt vmcnt(" #n ")" ::: "memory")
; #define PG8_WAIT_L(n) asm volatile("s_waitcnt lgkmcnt(" #n ")" ::: "memory")
; #define PG8_BAR __builtin_amdgcn_s_barrier()
; #define PG8_SCHED __builtin_amdgcn_sched_barrier(0)
; template <class Epi, class Sched, bool ALIGN_EPI = false, bool SP2 = false>
; __device__ __forceinline__ void gemm_phase(PG8_LAS unsigned char* lds, const Gemm g, const Sched& S, const Epi& E) {
;     ...
;             PG8_WAIT_V(8); PG8_WAIT_L(0); PG8_BAR; PG8_MMA(1, 0, At, B0); PG8_MMA(1, 1, At, B1); PG8_BAR; PG8_SCHED;
;             PG8_LDB(B0, 1, 0); PG8_LDB(B1, 1, 1); PG8_SCHED; PG8_LDA(At, 1, 0); PG8_STAGE(PG8_SA(0, 1), a2 + hstep, voffA);
;             PG8_WAIT_V(8); PG8_WAIT_L(0); PG8_BAR; PG8_MMA(0, 0, At, B0); PG8_MMA(0, 1, At, B1); PG8_BAR; PG8_SCHED;
	v_mfma_f32_16x16x32_bf16 v[62:65], v[162:165], v[212:215], v[62:65]
	v_mfma_f32_16x16x32_bf16 v[58:61], v[170:173], v[212:215], v[58:61]
	v_mfma_f32_16x16x32_bf16 v[46:49], v[162:165], v[220:223], v[46:49]
	v_mfma_f32_16x16x32_bf16 v[42:45], v[170:173], v[220:223], v[42:45]
	v_mfma_f32_16x16x32_bf16 v[30:33], v[162:165], v[228:231], v[30:33]
	v_mfma_f32_16x16x32_bf16 v[26:29], v[170:173], v[228:231], v[26:29]
	v_mfma_f32_16x16x32_bf16 v[14:17], v[162:165], v[236:239], v[14:17]
	v_mfma_f32_16x16x32_bf16 v[10:13], v[170:173], v[236:239], v[10:13]
	s_setprio 0
	s_setprio 1
	v_mfma_f32_16x16x32_bf16 v[62:65], v[166:169], v[216:219], v[62:65]
	v_mfma_f32_16x16x32_bf16 v[58:61], v[174:177], v[216:219], v[58:61]
	v_mfma_f32_16x16x32_bf16 v[46:49], v[166:169], v[224:227], v[46:49]
	v_mfma_f32_16x16x32_bf16 v[42:45], v[174:177], v[224:227], v[42:45]
	v_mfma_f32_16x16x32_bf16 v[30:33], v[166:169], v[232:235], v[30:33]
	v_mfma_f32_16x16x32_bf16 v[26:29], v[174:177], v[232:235], v[26:29]
	v_mfma_f32_16x16x32_bf16 v[14:17], v[166:169], v[240:243], v[14:17]
	v_mfma_f32_16x16x32_bf16 v[10:13], v[174:177], v[240:243], v[10:13]
	s_setprio 0
	s_setprio 1
	v_mfma_f32_16x16x32_bf16 v[54:57], v[178:181], v[212:215], v[54:57]
	v_mfma_f32_16x16x32_bf16 v[50:53], v[204:207], v[212:215], v[50:53]
	v_mfma_f32_16x16x32_bf16 v[38:41], v[178:181], v[220:223], v[38:41]
	v_mfma_f32_16x16x32_bf16 v[34:37], v[204:207], v[220:223], v[34:37]
	v_mfma_f32_16x16x32_bf16 v[22:25], v[178:181], v[228:231], v[22:25]
	v_mfma_f32_16x16x32_bf16 v[18:21], v[204:207], v[228:231], v[18:21]
	v_mfma_f32_16x16x32_bf16 v[6:9], v[178:181], v[236:239], v[6:9]
	v_mfma_f32_16x16x32_bf16 v[2:5], v[204:207], v[236:239], v[2:5]
	s_setprio 0
	s_setprio 1
	v_mfma_f32_16x16x32_bf16 v[54:57], v[182:185], v[216:219], v[54:57]
	v_mfma_f32_16x16x32_bf16 v[50:53], v[208:211], v[216:219], v[50:53]
	v_mfma_f32_16x16x32_bf16 v[38:41], v[182:185], v[224:227], v[38:41]
	v_mfma_f32_16x16x32_bf16 v[34:37], v[208:211], v[224:227], v[34:37]
	s_setprio 0
	v_mfma_f32_16x16x32_bf16 v[22:25], v[182:185], v[232:235], v[22:25]
	v_mfma_f32_16x16x32_bf16 v[18:21], v[208:211], v[232:235], v[18:21]
	v_mfma_f32_16x16x32_bf16 v[6:9], v[182:185], v[240:243], v[6:9]
	v_mfma_f32_16x16x32_bf16 v[2:5], v[208:211], v[240:243], v[2:5]
	s_barrier
	s_add_i32 s47, 0, 0x18000
	s_add_i32 s76, 0, 0x1c000
	v_add_u32_e32 v174, s47, v143
	v_add_u32_e32 v203, s76, v143
	ds_read_b128 v[162:165], v174
	ds_read_b128 v[166:169], v174 offset:1024
	ds_read_b128 v[170:173], v174 offset:2048
	ds_read_b128 v[174:177], v174 offset:3072
	ds_read_b128 v[178:181], v203
	ds_read_b128 v[182:185], v203 offset:1024
	ds_read_b128 v[204:207], v203 offset:2048
	ds_read_b128 v[208:211], v203 offset:3072
	s_add_u32 s58, s58, 0x80000
	s_addc_u32 s59, s59, 0
	s_mov_b32 m0, s67
	v_lshl_add_u64 v[248:249], s[58:59], 0, v[150:151]
	ds_read_b128 v[212:215], v161 offset:32768
	ds_read_b128 v[216:219], v161 offset:33792
	ds_read_b128 v[220:223], v161 offset:34816
	ds_read_b128 v[224:227], v161 offset:35840
	ds_read_b128 v[228:231], v161 offset:36864
	ds_read_b128 v[232:235], v161 offset:37888
	ds_read_b128 v[236:239], v161 offset:38912
	ds_read_b128 v[240:243], v161 offset:39936
	global_load_lds_dwordx4 v[248:249], off
	v_lshl_add_u64 v[248:249], s[58:59], 0, v[146:147]
	s_mov_b32 m0, s4
	s_nop 0
	global_load_lds_dwordx4 v[248:249], off
	s_setprio 1
	s_waitcnt vmcnt(8)
	s_waitcnt lgkmcnt(0)
	s_barrier
	v_mfma_f32_16x16x32_bf16 v[126:129], v[162:165], v[212:215], v[126:129]
	v_mfma_f32_16x16x32_bf16 v[122:125], v[170:173], v[212:215], v[122:125]
	v_mfma_f32_16x16x32_bf16 v[110:113], v[162:165], v[220:223], v[110:113]
	v_mfma_f32_16x16x32_bf16 v[106:109], v[170:173], v[220:223], v[106:109]
	v_mfma_f32_16x16x32_bf16 v[94:97], v[162:165], v[228:231], v[94:97]
	v_mfma_f32_16x16x32_bf16 v[90:93], v[170:173], v[228:231], v[90:93]
	v_mfma_f32_16x16x32_bf16 v[78:81], v[162:165], v[236:239], v[78:81]
	v_mfma_f32_16x16x32_bf16 v[74:77], v[170:173], v[236:239], v[74:77]
	s_setprio 0
	s_setprio 1
	v_mfma_f32_16x16x32_bf16 v[126:129], v[166:169], v[216:219], v[126:129]
	v_mfma_f32_16x16x32_bf16 v[122:125], v[174:177], v[216:219], v[122:125]
	v_mfma_f32_16x16x32_bf16 v[110:113], v[166:169], v[224:227], v[110:113]
	v_mfma_f32_16x16x32_bf16 v[106:109], v[174:177], v[224:227], v[106:109]
	v_mfma_f32_16x16x32_bf16 v[94:97], v[166:169], v[232:235], v[94:97]
	v_mfma_f32_16x16x32_bf16 v[90:93], v[174:177], v[232:235], v[90:93]
	v_mfma_f32_16x16x32_bf16 v[78:81], v[166:169], v[240:243], v[78:81]
	v_mfma_f32_16x16x32_bf16 v[74:77], v[174:177], v[240:243], v[74:77]
	s_setprio 0
	s_setprio 1
	v_mfma_f32_16x16x32_bf16 v[118:121], v[178:181], v[212:215], v[118:121]
	v_mfma_f32_16x16x32_bf16 v[114:117], v[204:207], v[212:215], v[114:117]
	v_mfma_f32_16x16x32_bf16 v[102:105], v[178:181], v[220:223], v[102:105]
	v_mfma_f32_16x16x32_bf16 v[98:101], v[204:207], v[220:223], v[98:101]
	v_mfma_f32_16x16x32_bf16 v[86:89], v[178:181], v[228:231], v[86:89]
	v_mfma_f32_16x16x32_bf16 v[82:85], v[204:207], v[228:231], v[82:85]
	v_mfma_f32_16x16x32_bf16 v[70:73], v[178:181], v[236:239], v[70:73]
	v_mfma_f32_16x16x32_bf16 v[66:69], v[204:207], v[236:239], v[66:69]
	s_setprio 0
	s_setprio 1
	v_mfma_f32_16x16x32_bf16 v[118:121], v[182:185], v[216:219], v[118:121]
	v_mfma_f32_16x16x32_bf16 v[114:117], v[208:211], v[216:219], v[114:117]
	v_mfma_f32_16x16x32_bf16 v[102:105], v[182:185], v[224:227], v[102:105]
	v_mfma_f32_16x16x32_bf16 v[98:101], v[208:211], v[224:227], v[98:101]
	s_setprio 0
	v_mfma_f32_16x16x32_bf16 v[86:89], v[182:185], v[232:235], v[86:89]
	v_mfma_f32_16x16x32_bf16 v[82:85], v[208:211], v[232:235], v[82:85]
	v_mfma_f32_16x16x32_bf16 v[70:73], v[182:185], v[240:243], v[70:73]
	v_mfma_f32_16x16x32_bf16 v[66:69], v[208:211], v[240:243], v[66:69]
	s_barrier
; #define PG8_STAGE(bufoff, gbase, voff) do { _Pragma("unroll") for (int _i = 0; _i < 2; ++_i) \
;         __builtin_amdgcn_global_load_lds((const unsigned*)((const char*)(gbase) + (voff)[_i]), (PG8_LAS unsigned*)(lds + (bufoff) + ldsw + _i * 8192), 16, 0, 0); } while (0)
; #define PG8_LDA(dst, b, h) do { _Pragma("unroll") for (int m = 0; m < 4; ++m) _Pragma("unroll") for (int k = 0; k < 2; ++k) dst[m][k] = *(const PG8_LAS bf16x8*)(lds + PG8_SA(b, h) + aoff + m * 2048 + k * 1024); } while (0)
; #define PG8_MMA(ai, bj, At, Bt) do { __builtin_amdgcn_s_setprio(1); _Pragma("unroll") for (int m = 0; m < 4; ++m) _Pragma("unroll") for (int n = 0; n < 2; ++n) _Pragma("unroll") for (int k = 0; k < 2; ++k) \
;         acc[ai][bj][m][n] = __builtin_amdgcn_mfma_f32_16x16x32_bf16(Bt[n][k], At[m][k], acc[ai][bj][m][n], 0, 0, 0); __builtin_amdgcn_s_setprio(0); } while (0)
; #define PG8_WAIT_V(n) asm volatile("s_waitcnt vmcnt(" #n ")" ::: "memory")
; #define PG8_WAIT_L(n) asm volatile("s_waitcnt lgkmcnt(" #n ")" ::: "memory")
; #define PG8_BAR __builtin_amdgcn_s_barrier()
; #define PG8_SCHED __builtin_amdgcn_sched_barrier(0)
; template <class Epi, class Sched, bool ALIGN_EPI = false, bool SP2 = false>
; __device__ __forceinline__ void gemm_phase(PG8_LAS unsigned char* lds, const Gemm g, const Sched& S, const Epi& E) {
;     ...
;             PG8_LDA(At, 1, 1); PG8_STAGE(PG8_SB(1, 0), b3, voffB); PG8_STAGE(PG8_SB(1, 1), b3 + hstep, voffB); PG8_STAGE(PG8_SA(1, 0), a3, voffA);
;             PG8_WAIT_V(8); PG8_WAIT_L(0); PG8_BAR; PG8_MMA(1, 0, At, B0); PG8_MMA(1, 1, At, B1); PG8_BAR; PG8_SCHED;
;     ...
;         if constexpr (ALIGN_EPI) { if (wr == 0) PG8_BAR; }
	s_add_i32 s47, s47, s54
	v_lshl_add_u64 v[158:159], v[158:159], 0, s[68:69]
	s_mov_b32 m0, s47
	ds_read_b128 v[212:215], v161 offset:49152
	ds_read_b128 v[216:219], v161 offset:50176
	ds_read_b128 v[220:223], v161 offset:51200
	ds_read_b128 v[224:227], v161 offset:52224
	ds_read_b128 v[228:231], v161 offset:53248
	ds_read_b128 v[232:235], v161 offset:54272
	ds_read_b128 v[236:239], v161 offset:55296
	ds_read_b128 v[240:243], v161 offset:56320
	global_load_lds_dwordx4 v[158:159], off
	s_add_i32 m0, s47, 0x2000
	s_add_u32 s18, s18, 0x80080
	v_lshl_add_u64 v[158:159], v[186:187], 0, s[68:69]
	s_addc_u32 s19, s19, 0
	s_add_i32 s47, s76, s54
	global_load_lds_dwordx4 v[158:159], off
	v_lshl_add_u64 v[158:159], s[18:19], 0, v[148:149]
	s_mov_b32 m0, s47
	s_nop 0
	global_load_lds_dwordx4 v[158:159], off
	v_lshl_add_u64 v[158:159], s[18:19], 0, v[144:145]
	s_add_i32 m0, s47, 0x2000
	s_nop 0
	global_load_lds_dwordx4 v[158:159], off
	v_lshl_add_u64 v[158:159], v[244:245], 0, s[68:69]
	s_mov_b32 m0, s5
	s_nop 0
	global_load_lds_dwordx4 v[158:159], off
	v_lshl_add_u64 v[158:159], v[246:247], 0, s[68:69]
	s_mov_b32 m0, s57
	s_nop 0
	global_load_lds_dwordx4 v[158:159], off
	s_nop 0
	s_setprio 1
	s_waitcnt vmcnt(8)
	s_waitcnt lgkmcnt(0)
	s_barrier
	v_mfma_f32_16x16x32_bf16 v[62:65], v[162:165], v[212:215], v[62:65]
	v_mfma_f32_16x16x32_bf16 v[58:61], v[170:173], v[212:215], v[58:61]
	v_mfma_f32_16x16x32_bf16 v[46:49], v[162:165], v[220:223], v[46:49]
	v_mfma_f32_16x16x32_bf16 v[42:45], v[170:173], v[220:223], v[42:45]
	v_mfma_f32_16x16x32_bf16 v[30:33], v[162:165], v[228:231], v[30:33]
	v_mfma_f32_16x16x32_bf16 v[26:29], v[170:173], v[228:231], v[26:29]
	v_mfma_f32_16x16x32_bf16 v[14:17], v[162:165], v[236:239], v[14:17]
	v_mfma_f32_16x16x32_bf16 v[10:13], v[170:173], v[236:239], v[10:13]
	s_setprio 0
	s_setprio 1
	v_mfma_f32_16x16x32_bf16 v[62:65], v[166:169], v[216:219], v[62:65]
	v_mfma_f32_16x16x32_bf16 v[58:61], v[174:177], v[216:219], v[58:61]
	v_mfma_f32_16x16x32_bf16 v[46:49], v[166:169], v[224:227], v[46:49]
	v_mfma_f32_16x16x32_bf16 v[42:45], v[174:177], v[224:227], v[42:45]
	v_mfma_f32_16x16x32_bf16 v[30:33], v[166:169], v[232:235], v[30:33]
	v_mfma_f32_16x16x32_bf16 v[26:29], v[174:177], v[232:235], v[26:29]
	v_mfma_f32_16x16x32_bf16 v[14:17], v[166:169], v[240:243], v[14:17]
	v_mfma_f32_16x16x32_bf16 v[10:13], v[174:177], v[240:243], v[10:13]
	s_setprio 0
	s_setprio 1
	v_mfma_f32_16x16x32_bf16 v[54:57], v[178:181], v[212:215], v[54:57]
	v_mfma_f32_16x16x32_bf16 v[50:53], v[204:207], v[212:215], v[50:53]
	v_mfma_f32_16x16x32_bf16 v[38:41], v[178:181], v[220:223], v[38:41]
	v_mfma_f32_16x16x32_bf16 v[34:37], v[204:207], v[220:223], v[34:37]
	v_mfma_f32_16x16x32_bf16 v[22:25], v[178:181], v[228:231], v[22:25]
	v_mfma_f32_16x16x32_bf16 v[18:21], v[204:207], v[228:231], v[18:21]
	v_mfma_f32_16x16x32_bf16 v[6:9], v[178:181], v[236:239], v[6:9]
	v_mfma_f32_16x16x32_bf16 v[2:5], v[204:207], v[236:239], v[2:5]
	s_setprio 0
	s_setprio 1
	v_mfma_f32_16x16x32_bf16 v[54:57], v[182:185], v[216:219], v[54:57]
	v_mfma_f32_16x16x32_bf16 v[50:53], v[208:211], v[216:219], v[50:53]
	v_mfma_f32_16x16x32_bf16 v[38:41], v[182:185], v[224:227], v[38:41]
	v_mfma_f32_16x16x32_bf16 v[34:37], v[208:211], v[224:227], v[34:37]
	s_setprio 0
	v_mfma_f32_16x16x32_bf16 v[22:25], v[182:185], v[232:235], v[22:25]
	v_mfma_f32_16x16x32_bf16 v[18:21], v[208:211], v[232:235], v[18:21]
	v_mfma_f32_16x16x32_bf16 v[6:9], v[182:185], v[240:243], v[6:9]
	v_mfma_f32_16x16x32_bf16 v[2:5], v[208:211], v[240:243], v[2:5]
	s_barrier
	s_add_i32 s46, s46, 2
	s_add_u32 s0, s0, 0x100
	s_addc_u32 s1, s1, 0
	s_add_u32 s78, s78, 0x100
	s_addc_u32 s79, s79, 0
	s_cmp_gt_u32 s46, 29
	s_cbranch_scc0 .LBB0_76
	s_and_b64 vcc, exec, s[42:43]
	s_cbranch_vccz .LBB0_79
	s_barrier

; #define PG8_STAGE(bufoff, gbase, voff) do { _Pragma("unroll") for (int _i = 0; _i < 2; ++_i) \
;         __builtin_amdgcn_global_load_lds((const unsigned*)((const char*)(gbase) + (voff)[_i]), (PG8_LAS unsigned*)(lds + (bufoff) + ldsw + _i * 8192), 16, 0, 0); } while (0)
; #define PG8_LDA(dst, b, h) do { _Pragma("unroll") for (int m = 0; m < 4; ++m) _Pragma("unroll") for (int k = 0; k < 2; ++k) dst[m][k] = *(const PG8_LAS bf16x8*)(lds + PG8_SA(b, h) + aoff + m * 2048 + k * 1024); } while (0)
; #define PG8_LDB(dst, b, h) do { _Pragma("unroll") for (int n = 0; n < 2; ++n) _Pragma("unroll") for (int k = 0; k < 2; ++k) dst[n][k] = *(const PG8_LAS bf16x8*)(lds + PG8_SB(b, h) + boff + n * 2048 + k * 1024); } while (0)
; #define PG8_WAIT_V(n) asm volatile("s_waitcnt vmcnt(" #n ")" ::: "memory")
; #define PG8_WAIT_L(n) asm volatile("s_waitcnt lgkmcnt(" #n ")" ::: "memory")
; #define PG8_BAR __builtin_amdgcn_s_barrier()
; #define PG8_SCHED __builtin_amdgcn_sched_barrier(0)
; template <class Epi, class Sched, bool ALIGN_EPI = false, bool SP2 = false>
; __device__ __forceinline__ void gemm_phase(PG8_LAS unsigned char* lds, const Gemm g, const Sched& S, const Epi& E) {
;     ...
;         const char* nA = has_next ? (const char*)g.A + (size_t)nxt.pm * tstep : cA; const char* nB = has_next ? (const char*)g.Bt + (size_t)nxt.pn * tstep : cB;
;         for (int t = 0; t < nt; t += 2) {
;             const bool last = (t == nt - 2);
;             const char* a1 = cA + (size_t)(t + 1) * kstep;
;             const char* a2 = last ? nA : cA + (size_t)(t + 2) * kstep; const char* b2 = last ? nB : cB + (size_t)(t + 2) * kstep;
;             const char* a3 = a2 + kstep; const char* b3 = b2 + kstep;
;             if (last && has_next) S.a_ready(nxt);
;             if constexpr (SP2) {
;             PG8_LDB(B0, 0, 0); PG8_LDB(B1, 0, 1); PG8_SCHED; PG8_LDA(At, 0, 0); PG8_STAGE(PG8_SA(1, 1), a1 + hstep, voffA);
;             PG8_WAIT_V(8); PG8_WAIT_L(0); PG8_BAR; PG8_MMA(0, 0, At, B0); PG8_MMA(0, 1, At, B1); PG8_BAR; PG8_SCHED;
;             PG8_LDA(At, 0, 1); PG8_STAGE(PG8_SB(0, 0), b2, voffB); PG8_STAGE(PG8_SB(0, 1), b2 + hstep, voffB); PG8_STAGE(PG8_SA(0, 0), a2, voffA);
;             PG8_WAIT_V(8); PG8_WAIT_L(0); PG8_BAR; PG8_MMA(1, 0, At, B0); PG8_MMA(1, 1, At, B1); PG8_BAR; PG8_SCHED;
.LBB0_98:
	s_add_u32 s40, vcc_lo, 0xfff80080
	s_addc_u32 s41, vcc_hi, -1
	s_add_i32 s47, 0, 0x10000
	s_cmp_eq_u32 s46, 28
	s_cselect_b32 s59, s97, s41
	s_cselect_b32 s58, s84, s40
	s_cselect_b32 s41, s85, s79
	s_cselect_b32 s40, s95, s78
	s_add_i32 s80, 0, 0x14000
	v_add_u32_e32 v170, s47, v143
	v_add_u32_e32 v186, s80, v143
	ds_read_b128 v[156:159], v170
	ds_read_b128 v[162:165], v170 offset:1024
	ds_read_b128 v[166:169], v170 offset:2048
	ds_read_b128 v[170:173], v170 offset:3072
	ds_read_b128 v[174:177], v186
	ds_read_b128 v[178:181], v186 offset:1024
	ds_read_b128 v[182:185], v186 offset:2048
	ds_read_b128 v[204:207], v186 offset:3072
	v_lshl_add_u64 v[186:187], vcc, 0, v[152:153]
	s_add_i32 m0, s5, 0xc000
	ds_read_b128 v[208:211], v161
	ds_read_b128 v[212:215], v161 offset:1024
	ds_read_b128 v[216:219], v161 offset:2048
	ds_read_b128 v[220:223], v161 offset:3072
	ds_read_b128 v[224:227], v161 offset:4096
	ds_read_b128 v[228:231], v161 offset:5120
	ds_read_b128 v[232:235], v161 offset:6144
	ds_read_b128 v[236:239], v161 offset:7168
	global_load_lds_dwordx4 v[186:187], off
	v_lshl_add_u64 v[186:187], vcc, 0, v[154:155]
	s_add_i32 m0, s5, 0xe000
	s_nop 0
	global_load_lds_dwordx4 v[186:187], off
	s_setprio 1
	s_waitcnt vmcnt(8)
	s_waitcnt lgkmcnt(0)
	s_barrier
	v_mfma_f32_16x16x32_bf16 v[126:129], v[156:159], v[208:211], v[126:129]
	v_mfma_f32_16x16x32_bf16 v[122:125], v[166:169], v[208:211], v[122:125]
	v_mfma_f32_16x16x32_bf16 v[110:113], v[156:159], v[216:219], v[110:113]
	v_mfma_f32_16x16x32_bf16 v[106:109], v[166:169], v[216:219], v[106:109]
	v_mfma_f32_16x16x32_bf16 v[94:97], v[156:159], v[224:227], v[94:97]
	v_mfma_f32_16x16x32_bf16 v[90:93], v[166:169], v[224:227], v[90:93]
	v_mfma_f32_16x16x32_bf16 v[78:81], v[156:159], v[232:235], v[78:81]
	v_mfma_f32_16x16x32_bf16 v[74:77], v[166:169], v[232:235], v[74:77]
	s_setprio 0
	s_setprio 1
	v_mfma_f32_16x16x32_bf16 v[126:129], v[162:165], v[212:215], v[126:129]
	v_mfma_f32_16x16x32_bf16 v[122:125], v[170:173], v[212:215], v[122:125]
	v_mfma_f32_16x16x32_bf16 v[110:113], v[162:165], v[220:223], v[110:113]
	v_mfma_f32_16x16x32_bf16 v[106:109], v[170:173], v[220:223], v[106:109]
	v_mfma_f32_16x16x32_bf16 v[94:97], v[162:165], v[228:231], v[94:97]
	v_mfma_f32_16x16x32_bf16 v[90:93], v[170:173], v[228:231], v[90:93]
	v_mfma_f32_16x16x32_bf16 v[78:81], v[162:165], v[236:239], v[78:81]
	v_mfma_f32_16x16x32_bf16 v[74:77], v[170:173], v[236:239], v[74:77]
	s_setprio 0
	s_setprio 1
	v_mfma_f32_16x16x32_bf16 v[118:121], v[174:177], v[208:211], v[118:121]
	v_mfma_f32_16x16x32_bf16 v[114:117], v[182:185], v[208:211], v[114:117]
	v_mfma_f32_16x16x32_bf16 v[102:105], v[174:177], v[216:219], v[102:105]
	v_mfma_f32_16x16x32_bf16 v[98:101], v[182:185], v[216:219], v[98:101]
	v_mfma_f32_16x16x32_bf16 v[86:89], v[174:177], v[224:227], v[86:89]
	v_mfma_f32_16x16x32_bf16 v[82:85], v[182:185], v[224:227], v[82:85]
	v_mfma_f32_16x16x32_bf16 v[70:73], v[174:177], v[232:235], v[70:73]
	v_mfma_f32_16x16x32_bf16 v[66:69], v[182:185], v[232:235], v[66:69]
	s_setprio 0
	s_setprio 1
	v_mfma_f32_16x16x32_bf16 v[118:121], v[178:181], v[212:215], v[118:121]
	v_mfma_f32_16x16x32_bf16 v[114:117], v[204:207], v[212:215], v[114:117]
	v_mfma_f32_16x16x32_bf16 v[102:105], v[178:181], v[220:223], v[102:105]
	v_mfma_f32_16x16x32_bf16 v[98:101], v[204:207], v[220:223], v[98:101]
	s_setprio 0
	v_mfma_f32_16x16x32_bf16 v[86:89], v[178:181], v[228:231], v[86:89]
	v_mfma_f32_16x16x32_bf16 v[82:85], v[204:207], v[228:231], v[82:85]
	v_mfma_f32_16x16x32_bf16 v[70:73], v[178:181], v[236:239], v[70:73]
	v_mfma_f32_16x16x32_bf16 v[66:69], v[204:207], v[236:239], v[66:69]
	s_barrier
	s_add_i32 s47, s47, s4
	v_lshl_add_u64 v[186:187], s[40:41], 0, v[148:149]
	s_mov_b32 m0, s47
	ds_read_b128 v[208:211], v161 offset:16384
	ds_read_b128 v[212:215], v161 offset:17408
	ds_read_b128 v[216:219], v161 offset:18432
	ds_read_b128 v[220:223], v161 offset:19456
	ds_read_b128 v[224:227], v161 offset:20480
	ds_read_b128 v[228:231], v161 offset:21504
	ds_read_b128 v[232:235], v161 offset:22528
	ds_read_b128 v[236:239], v161 offset:23552
	global_load_lds_dwordx4 v[186:187], off
	s_add_i32 m0, s47, 0x2000
	s_add_u32 s76, s40, 0x80000
	v_lshl_add_u64 v[240:241], s[40:41], 0, v[144:145]
	s_addc_u32 s77, s41, 0
	s_add_i32 s47, s80, s4
	global_load_lds_dwordx4 v[240:241], off
	v_lshl_add_u64 v[242:243], s[76:77], 0, v[148:149]
	s_mov_b32 m0, s47
	v_lshl_add_u64 v[244:245], s[58:59], 0, v[146:147]
	global_load_lds_dwordx4 v[242:243], off
	v_lshl_add_u64 v[242:243], s[76:77], 0, v[144:145]
	s_add_i32 m0, s47, 0x2000
	s_nop 0
	global_load_lds_dwordx4 v[242:243], off
	v_lshl_add_u64 v[242:243], s[58:59], 0, v[150:151]
	s_mov_b32 m0, s5
	s_nop 0
	global_load_lds_dwordx4 v[242:243], off
	s_mov_b32 m0, s30
	s_nop 0
	global_load_lds_dwordx4 v[244:245], off
	s_setprio 1
	s_waitcnt vmcnt(8)
	s_waitcnt lgkmcnt(0)
	s_barrier
; #define PG8_STAGE(bufoff, gbase, voff) do { _Pragma("unroll") for (int _i = 0; _i < 2; ++_i) \
;         __builtin_amdgcn_global_load_lds((const unsigned*)((const char*)(gbase) + (voff)[_i]), (PG8_LAS unsigned*)(lds + (bufoff) + ldsw + _i * 8192), 16, 0, 0); } while (0)
; #define PG8_LDA(dst, b, h) do { _Pragma("unroll") for (int m = 0; m < 4; ++m) _Pragma("unroll") for (int k = 0; k < 2; ++k) dst[m][k] = *(const PG8_LAS bf16x8*)(lds + PG8_SA(b, h) + aoff + m * 2048 + k * 1024); } while (0)
; #define PG8_LDB(dst, b, h) do { _Pragma("unroll") for (int n = 0; n < 2; ++n) _Pragma("unroll") for (int k = 0; k < 2; ++k) dst[n][k] = *(const PG8_LAS bf16x8*)(lds + PG8_SB(b, h) + boff + n * 2048 + k * 1024); } while (0)
; #define PG8_MMA(ai, bj, At, Bt) do { __builtin_amdgcn_s_setprio(1); _Pragma("unroll") for (int m = 0; m < 4; ++m) _Pragma("unroll") for (int n = 0; n < 2; ++n) _Pragma("unroll") for (int k = 0; k < 2; ++k) \
;         acc[ai][bj][m][n] = __builtin_amdgcn_mfma_f32_16x16x32_bf16(Bt[n][k], At[m][k], acc[ai][bj][m][n], 0, 0, 0); __builtin_amdgcn_s_setprio(0); } while (0)
; #define PG8_WAIT_V(n) asm volatile("s_waitcnt vmcnt(" #n ")" ::: "memory")
; #define PG8_WAIT_L(n) asm volatile("s_waitcnt lgkmcnt(" #n ")" ::: "memory")
; #define PG8_BAR __builtin_amdgcn_s_barrier()
; #define PG8_SCHED __builtin_amdgcn_sched_barrier(0)
; template <class Epi, class Sched, bool ALIGN_EPI = false, bool SP2 = false>
; __device__ __forceinline__ void gemm_phase(PG8_LAS unsigned char* lds, const Gemm g, const Sched& S, const Epi& E) {
;     ...
;             PG8_WAIT_V(8); PG8_WAIT_L(0); PG8_BAR; PG8_MMA(1, 0, At, B0); PG8_MMA(1, 1, At, B1); PG8_BAR; PG8_SCHED;
;             PG8_LDB(B0, 1, 0); PG8_LDB(B1, 1, 1); PG8_SCHED; PG8_LDA(At, 1, 0); PG8_STAGE(PG8_SA(0, 1), a2 + hstep, voffA);
;             PG8_WAIT_V(8); PG8_WAIT_L(0); PG8_BAR; PG8_MMA(0, 0, At, B0); PG8_MMA(0, 1, At, B1); PG8_BAR; PG8_SCHED;
	v_mfma_f32_16x16x32_bf16 v[62:65], v[156:159], v[208:211], v[62:65]
	v_mfma_f32_16x16x32_bf16 v[58:61], v[166:169], v[208:211], v[58:61]
	v_mfma_f32_16x16x32_bf16 v[46:49], v[156:159], v[216:219], v[46:49]
	v_mfma_f32_16x16x32_bf16 v[42:45], v[166:169], v[216:219], v[42:45]
	v_mfma_f32_16x16x32_bf16 v[30:33], v[156:159], v[224:227], v[30:33]
	v_mfma_f32_16x16x32_bf16 v[26:29], v[166:169], v[224:227], v[26:29]
	v_mfma_f32_16x16x32_bf16 v[14:17], v[156:159], v[232:235], v[14:17]
	v_mfma_f32_16x16x32_bf16 v[10:13], v[166:169], v[232:235], v[10:13]
	s_setprio 0
	s_setprio 1
	v_mfma_f32_16x16x32_bf16 v[62:65], v[162:165], v[212:215], v[62:65]
	v_mfma_f32_16x16x32_bf16 v[58:61], v[170:173], v[212:215], v[58:61]
	v_mfma_f32_16x16x32_bf16 v[46:49], v[162:165], v[220:223], v[46:49]
	v_mfma_f32_16x16x32_bf16 v[42:45], v[170:173], v[220:223], v[42:45]
	v_mfma_f32_16x16x32_bf16 v[30:33], v[162:165], v[228:231], v[30:33]
	v_mfma_f32_16x16x32_bf16 v[26:29], v[170:173], v[228:231], v[26:29]
	v_mfma_f32_16x16x32_bf16 v[14:17], v[162:165], v[236:239], v[14:17]
	v_mfma_f32_16x16x32_bf16 v[10:13], v[170:173], v[236:239], v[10:13]
	s_setprio 0
	s_setprio 1
	v_mfma_f32_16x16x32_bf16 v[54:57], v[174:177], v[208:211], v[54:57]
	v_mfma_f32_16x16x32_bf16 v[50:53], v[182:185], v[208:211], v[50:53]
	v_mfma_f32_16x16x32_bf16 v[38:41], v[174:177], v[216:219], v[38:41]
	v_mfma_f32_16x16x32_bf16 v[34:37], v[182:185], v[216:219], v[34:37]
	v_mfma_f32_16x16x32_bf16 v[22:25], v[174:177], v[224:227], v[22:25]
	v_mfma_f32_16x16x32_bf16 v[18:21], v[182:185], v[224:227], v[18:21]
	v_mfma_f32_16x16x32_bf16 v[6:9], v[174:177], v[232:235], v[6:9]
	v_mfma_f32_16x16x32_bf16 v[2:5], v[182:185], v[232:235], v[2:5]
	s_setprio 0
	s_setprio 1
	v_mfma_f32_16x16x32_bf16 v[54:57], v[178:181], v[212:215], v[54:57]
	v_mfma_f32_16x16x32_bf16 v[50:53], v[204:207], v[212:215], v[50:53]
	v_mfma_f32_16x16x32_bf16 v[38:41], v[178:181], v[220:223], v[38:41]
	v_mfma_f32_16x16x32_bf16 v[34:37], v[204:207], v[220:223], v[34:37]
	s_setprio 0
	v_mfma_f32_16x16x32_bf16 v[22:25], v[178:181], v[228:231], v[22:25]
	v_mfma_f32_16x16x32_bf16 v[18:21], v[204:207], v[228:231], v[18:21]
	v_mfma_f32_16x16x32_bf16 v[6:9], v[178:181], v[236:239], v[6:9]
	v_mfma_f32_16x16x32_bf16 v[2:5], v[204:207], v[236:239], v[2:5]
	s_barrier
	s_add_i32 s47, 0, 0x18000
	s_add_i32 s76, 0, 0x1c000
	v_add_u32_e32 v170, s47, v143
	v_add_u32_e32 v203, s76, v143
	ds_read_b128 v[156:159], v170
	ds_read_b128 v[162:165], v170 offset:1024
	ds_read_b128 v[166:169], v170 offset:2048
	ds_read_b128 v[170:173], v170 offset:3072
	ds_read_b128 v[174:177], v203
	ds_read_b128 v[178:181], v203 offset:1024
	ds_read_b128 v[182:185], v203 offset:2048
	ds_read_b128 v[204:207], v203 offset:3072
	s_add_u32 s58, s58, 0x80000
	s_addc_u32 s59, s59, 0
	s_mov_b32 m0, s34
	v_lshl_add_u64 v[246:247], s[58:59], 0, v[150:151]
	ds_read_b128 v[208:211], v161 offset:32768
	ds_read_b128 v[212:215], v161 offset:33792
	ds_read_b128 v[216:219], v161 offset:34816
	ds_read_b128 v[220:223], v161 offset:35840
	ds_read_b128 v[224:227], v161 offset:36864
	ds_read_b128 v[228:231], v161 offset:37888
	ds_read_b128 v[232:235], v161 offset:38912
	ds_read_b128 v[236:239], v161 offset:39936
	global_load_lds_dwordx4 v[246:247], off
	v_lshl_add_u64 v[246:247], s[58:59], 0, v[146:147]
	s_mov_b32 m0, s57
	s_nop 0
	global_load_lds_dwordx4 v[246:247], off
	s_setprio 1
	s_waitcnt vmcnt(8)
	s_waitcnt lgkmcnt(0)
	s_barrier
	v_mfma_f32_16x16x32_bf16 v[126:129], v[156:159], v[208:211], v[126:129]
	v_mfma_f32_16x16x32_bf16 v[122:125], v[166:169], v[208:211], v[122:125]
	v_mfma_f32_16x16x32_bf16 v[110:113], v[156:159], v[216:219], v[110:113]
	v_mfma_f32_16x16x32_bf16 v[106:109], v[166:169], v[216:219], v[106:109]
	v_mfma_f32_16x16x32_bf16 v[94:97], v[156:159], v[224:227], v[94:97]
	v_mfma_f32_16x16x32_bf16 v[90:93], v[166:169], v[224:227], v[90:93]
	v_mfma_f32_16x16x32_bf16 v[78:81], v[156:159], v[232:235], v[78:81]
	v_mfma_f32_16x16x32_bf16 v[74:77], v[166:169], v[232:235], v[74:77]
	s_setprio 0
	s_setprio 1
	v_mfma_f32_16x16x32_bf16 v[126:129], v[162:165], v[212:215], v[126:129]
	v_mfma_f32_16x16x32_bf16 v[122:125], v[170:173], v[212:215], v[122:125]
	v_mfma_f32_16x16x32_bf16 v[110:113], v[162:165], v[220:223], v[110:113]
	v_mfma_f32_16x16x32_bf16 v[106:109], v[170:173], v[220:223], v[106:109]
	v_mfma_f32_16x16x32_bf16 v[94:97], v[162:165], v[228:231], v[94:97]
	v_mfma_f32_16x16x32_bf16 v[90:93], v[170:173], v[228:231], v[90:93]
	v_mfma_f32_16x16x32_bf16 v[78:81], v[162:165], v[236:239], v[78:81]
	v_mfma_f32_16x16x32_bf16 v[74:77], v[170:173], v[236:239], v[74:77]
	s_setprio 0
	s_setprio 1
	v_mfma_f32_16x16x32_bf16 v[118:121], v[174:177], v[208:211], v[118:121]
	v_mfma_f32_16x16x32_bf16 v[114:117], v[182:185], v[208:211], v[114:117]
	v_mfma_f32_16x16x32_bf16 v[102:105], v[174:177], v[216:219], v[102:105]
	v_mfma_f32_16x16x32_bf16 v[98:101], v[182:185], v[216:219], v[98:101]
	v_mfma_f32_16x16x32_bf16 v[86:89], v[174:177], v[224:227], v[86:89]
	v_mfma_f32_16x16x32_bf16 v[82:85], v[182:185], v[224:227], v[82:85]
	v_mfma_f32_16x16x32_bf16 v[70:73], v[174:177], v[232:235], v[70:73]
	v_mfma_f32_16x16x32_bf16 v[66:69], v[182:185], v[232:235], v[66:69]
	s_setprio 0
	s_setprio 1
	v_mfma_f32_16x16x32_bf16 v[118:121], v[178:181], v[212:215], v[118:121]
	v_mfma_f32_16x16x32_bf16 v[114:117], v[204:207], v[212:215], v[114:117]
	v_mfma_f32_16x16x32_bf16 v[102:105], v[178:181], v[220:223], v[102:105]
	v_mfma_f32_16x16x32_bf16 v[98:101], v[204:207], v[220:223], v[98:101]
	s_setprio 0
	v_mfma_f32_16x16x32_bf16 v[86:89], v[178:181], v[228:231], v[86:89]
	v_mfma_f32_16x16x32_bf16 v[82:85], v[204:207], v[228:231], v[82:85]
	v_mfma_f32_16x16x32_bf16 v[70:73], v[178:181], v[236:239], v[70:73]
	v_mfma_f32_16x16x32_bf16 v[66:69], v[204:207], v[236:239], v[66:69]
	s_barrier
; #define PG8_STAGE(bufoff, gbase, voff) do { _Pragma("unroll") for (int _i = 0; _i < 2; ++_i) \
;         __builtin_amdgcn_global_load_lds((const unsigned*)((const char*)(gbase) + (voff)[_i]), (PG8_LAS unsigned*)(lds + (bufoff) + ldsw + _i * 8192), 16, 0, 0); } while (0)
; #define PG8_LDA(dst, b, h) do { _Pragma("unroll") for (int m = 0; m < 4; ++m) _Pragma("unroll") for (int k = 0; k < 2; ++k) dst[m][k] = *(const PG8_LAS bf16x8*)(lds + PG8_SA(b, h) + aoff + m * 2048 + k * 1024); } while (0)
; #define PG8_MMA(ai, bj, At, Bt) do { __builtin_amdgcn_s_setprio(1); _Pragma("unroll") for (int m = 0; m < 4; ++m) _Pragma("unroll") for (int n = 0; n < 2; ++n) _Pragma("unroll") for (int k = 0; k < 2; ++k) \
;         acc[ai][bj][m][n] = __builtin_amdgcn_mfma_f32_16x16x32_bf16(Bt[n][k], At[m][k], acc[ai][bj][m][n], 0, 0, 0); __builtin_amdgcn_s_setprio(0); } while (0)
; #define PG8_WAIT_V(n) asm volatile("s_waitcnt vmcnt(" #n ")" ::: "memory")
; #define PG8_WAIT_L(n) asm volatile("s_waitcnt lgkmcnt(" #n ")" ::: "memory")
; #define PG8_BAR __builtin_amdgcn_s_barrier()
; #define PG8_SCHED __builtin_amdgcn_sched_barrier(0)
;     __device__ __forceinline__ void operator()(const f32x4 (&acc)[2][2][4][2], const Unit& u, int wr, int wc, int fr, int fq) const {
;     ...
;             for (int m = 0; m < 4; ++m) { const size_t row = (size_t)(row0 + ai * HALF + m * 16); float ss = 0.f;
; #pragma unroll
;                 for (int bj = 0; bj < 2; ++bj) { const size_t off = row * DM + col0 + bj * HALF;
;                     f32x4 v0 = acc[ai][bj][m][0] + *(const f32x4*)(base + off), v1 = acc[ai][bj][m][1] + *(const f32x4*)(base + off + 4);
; template <class Epi, class Sched, bool ALIGN_EPI = false, bool SP2 = false>
; __device__ __forceinline__ void gemm_phase(PG8_LAS unsigned char* lds, const Gemm g, const Sched& S, const Epi& E) {
;     ...
;             PG8_LDA(At, 1, 1); PG8_STAGE(PG8_SB(1, 0), b3, voffB); PG8_STAGE(PG8_SB(1, 1), b3 + hstep, voffB); PG8_STAGE(PG8_SA(1, 0), a3, voffA);
;             PG8_WAIT_V(8); PG8_WAIT_L(0); PG8_BAR; PG8_MMA(1, 0, At, B0); PG8_MMA(1, 1, At, B1); PG8_BAR; PG8_SCHED;
	s_add_i32 s47, s47, s4
	v_lshl_add_u64 v[186:187], v[186:187], 0, s[68:69]
	s_mov_b32 m0, s47
	ds_read_b128 v[208:211], v161 offset:49152
	ds_read_b128 v[212:215], v161 offset:50176
	ds_read_b128 v[216:219], v161 offset:51200
	ds_read_b128 v[220:223], v161 offset:52224
	ds_read_b128 v[224:227], v161 offset:53248
	ds_read_b128 v[228:231], v161 offset:54272
	ds_read_b128 v[232:235], v161 offset:55296
	ds_read_b128 v[236:239], v161 offset:56320
	global_load_lds_dwordx4 v[186:187], off
	s_add_i32 m0, s47, 0x2000
	s_add_u32 s40, s40, 0x80080
	v_lshl_add_u64 v[186:187], v[240:241], 0, s[68:69]
	s_addc_u32 s41, s41, 0
	s_add_i32 s47, s76, s4
	global_load_lds_dwordx4 v[186:187], off
	v_lshl_add_u64 v[186:187], s[40:41], 0, v[148:149]
	s_mov_b32 m0, s47
	s_nop 0
	global_load_lds_dwordx4 v[186:187], off
	v_lshl_add_u64 v[186:187], s[40:41], 0, v[144:145]
	s_add_i32 m0, s47, 0x2000
	s_nop 0
	global_load_lds_dwordx4 v[186:187], off
	v_lshl_add_u64 v[186:187], v[242:243], 0, s[68:69]
	s_mov_b32 m0, s67
	s_nop 0
	global_load_lds_dwordx4 v[186:187], off
	v_lshl_add_u64 v[186:187], v[244:245], 0, s[68:69]
	s_mov_b32 m0, s28
	s_nop 0
	global_load_lds_dwordx4 v[186:187], off
	s_nop 0
	s_setprio 1
	s_waitcnt vmcnt(8)
	s_waitcnt lgkmcnt(0)
	s_barrier
	v_mfma_f32_16x16x32_bf16 v[62:65], v[156:159], v[208:211], v[62:65]
	v_mfma_f32_16x16x32_bf16 v[58:61], v[166:169], v[208:211], v[58:61]
	v_mfma_f32_16x16x32_bf16 v[46:49], v[156:159], v[216:219], v[46:49]
	v_mfma_f32_16x16x32_bf16 v[42:45], v[166:169], v[216:219], v[42:45]
	v_mfma_f32_16x16x32_bf16 v[30:33], v[156:159], v[224:227], v[30:33]
	v_mfma_f32_16x16x32_bf16 v[26:29], v[166:169], v[224:227], v[26:29]
	v_mfma_f32_16x16x32_bf16 v[14:17], v[156:159], v[232:235], v[14:17]
	v_mfma_f32_16x16x32_bf16 v[10:13], v[166:169], v[232:235], v[10:13]
	s_setprio 0
	s_setprio 1
	v_mfma_f32_16x16x32_bf16 v[62:65], v[162:165], v[212:215], v[62:65]
	v_mfma_f32_16x16x32_bf16 v[58:61], v[170:173], v[212:215], v[58:61]
	v_mfma_f32_16x16x32_bf16 v[46:49], v[162:165], v[220:223], v[46:49]
	v_mfma_f32_16x16x32_bf16 v[42:45], v[170:173], v[220:223], v[42:45]
	v_mfma_f32_16x16x32_bf16 v[30:33], v[162:165], v[228:231], v[30:33]
	v_mfma_f32_16x16x32_bf16 v[26:29], v[170:173], v[228:231], v[26:29]
	v_mfma_f32_16x16x32_bf16 v[14:17], v[162:165], v[236:239], v[14:17]
	v_mfma_f32_16x16x32_bf16 v[10:13], v[170:173], v[236:239], v[10:13]
	s_setprio 0
	s_setprio 1
	v_mfma_f32_16x16x32_bf16 v[54:57], v[174:177], v[208:211], v[54:57]
	v_mfma_f32_16x16x32_bf16 v[50:53], v[182:185], v[208:211], v[50:53]
	v_mfma_f32_16x16x32_bf16 v[38:41], v[174:177], v[216:219], v[38:41]
	v_mfma_f32_16x16x32_bf16 v[34:37], v[182:185], v[216:219], v[34:37]
	v_mfma_f32_16x16x32_bf16 v[22:25], v[174:177], v[224:227], v[22:25]
	v_mfma_f32_16x16x32_bf16 v[18:21], v[182:185], v[224:227], v[18:21]
	v_mfma_f32_16x16x32_bf16 v[6:9], v[174:177], v[232:235], v[6:9]
	v_mfma_f32_16x16x32_bf16 v[2:5], v[182:185], v[232:235], v[2:5]
	s_setprio 0
	s_setprio 1
	v_mfma_f32_16x16x32_bf16 v[54:57], v[178:181], v[212:215], v[54:57]
	v_mfma_f32_16x16x32_bf16 v[50:53], v[204:207], v[212:215], v[50:53]
	v_mfma_f32_16x16x32_bf16 v[38:41], v[178:181], v[220:223], v[38:41]
	v_mfma_f32_16x16x32_bf16 v[34:37], v[204:207], v[220:223], v[34:37]
	s_setprio 0
	v_mfma_f32_16x16x32_bf16 v[22:25], v[178:181], v[228:231], v[22:25]
	v_mfma_f32_16x16x32_bf16 v[18:21], v[204:207], v[228:231], v[18:21]
	v_mfma_f32_16x16x32_bf16 v[6:9], v[178:181], v[236:239], v[6:9]
	v_mfma_f32_16x16x32_bf16 v[2:5], v[204:207], v[236:239], v[2:5]
	s_barrier
	s_add_i32 s46, s46, 2
	s_add_u32 vcc_lo, vcc_lo, 0x100
	s_addc_u32 vcc_hi, vcc_hi, 0
	s_add_u32 s78, s78, 0x100
	s_addc_u32 s79, s79, 0
	s_cmp_gt_u32 s46, 29
	s_cbranch_scc0 .LBB0_98
	v_lshl_add_u32 v156, s73, 8, v1
	v_lshl_or_b32 v157, s54, 8, v160
	v_lshl_add_u32 v157, v156, 11, v157
	v_mov_b32_e32 v247, 0
	v_lshlrev_b32_e32 v246, 2, v157
	v_lshl_add_u64 v[162:163], s[8:9], 0, v[246:247]
	v_lshlrev_b32_e32 v246, 1, v157
	v_lshl_add_u64 v[244:245], s[70:71], 0, v[246:247]
	s_mov_b32 s41, 0
	global_load_dwordx4 v[164:167], v[162:163], off
	global_load_dwordx4 v[168:171], v[162:163], off offset:16
	global_load_dwordx4 v[172:175], v[162:163], off offset:512
	global_load_dwordx4 v[176:179], v[162:163], off offset:528
	s_mov_b32 s40, 0x20000
	v_lshl_add_u64 v[246:247], v[162:163], 0, s[40:41]
	global_load_dwordx4 v[180:183], v[246:247], off
	global_load_dwordx4 v[184:187], v[246:247], off offset:16
	global_load_dwordx4 v[204:207], v[246:247], off offset:512
	global_load_dwordx4 v[208:211], v[246:247], off offset:528
	s_mov_b32 s40, 0x40000
	v_lshl_add_u64 v[246:247], v[162:163], 0, s[40:41]
	global_load_dwordx4 v[212:215], v[246:247], off
	global_load_dwordx4 v[216:219], v[246:247], off offset:16
	global_load_dwordx4 v[220:223], v[246:247], off offset:512
	global_load_dwordx4 v[224:227], v[246:247], off offset:528
	s_mov_b32 s40, 0x60000
	v_lshl_add_u64 v[246:247], v[162:163], 0, s[40:41]
	global_load_dwordx4 v[228:231], v[246:247], off
	global_load_dwordx4 v[232:235], v[246:247], off offset:16
	global_load_dwordx4 v[236:239], v[246:247], off offset:512
	global_load_dwordx4 v[240:243], v[246:247], off offset:528
	s_and_b64 vcc, exec, s[36:37]
	s_cbranch_vccz .Lx1_nobar
	s_barrier

; #define PG8_STAGE(bufoff, gbase, voff) do { _Pragma("unroll") for (int _i = 0; _i < 2; ++_i) \
;         __builtin_amdgcn_global_load_lds((const unsigned*)((const char*)(gbase) + (voff)[_i]), (PG8_LAS unsigned*)(lds + (bufoff) + ldsw + _i * 8192), 16, 0, 0); } while (0)
; #define PG8_LDA(dst, b, h) do { _Pragma("unroll") for (int m = 0; m < 4; ++m) _Pragma("unroll") for (int k = 0; k < 2; ++k) dst[m][k] = *(const PG8_LAS bf16x8*)(lds + PG8_SA(b, h) + aoff + m * 2048 + k * 1024); } while (0)
; #define PG8_LDB(dst, b, h) do { _Pragma("unroll") for (int n = 0; n < 2; ++n) _Pragma("unroll") for (int k = 0; k < 2; ++k) dst[n][k] = *(const PG8_LAS bf16x8*)(lds + PG8_SB(b, h) + boff + n * 2048 + k * 1024); } while (0)
; #define PG8_MMA(ai, bj, At, Bt) do { __builtin_amdgcn_s_setprio(1); _Pragma("unroll") for (int m = 0; m < 4; ++m) _Pragma("unroll") for (int n = 0; n < 2; ++n) _Pragma("unroll") for (int k = 0; k < 2; ++k) \
;         acc[ai][bj][m][n] = __builtin_amdgcn_mfma_f32_16x16x32_bf16(Bt[n][k], At[m][k], acc[ai][bj][m][n], 0, 0, 0); __builtin_amdgcn_s_setprio(0); } while (0)
; #define PG8_WAIT_V(n) asm volatile("s_waitcnt vmcnt(" #n ")" ::: "memory")
; #define PG8_WAIT_L(n) asm volatile("s_waitcnt lgkmcnt(" #n ")" ::: "memory")
; template <class Epi, class Sched, bool ALIGN_EPI = false, bool SP2 = false>
; __device__ __forceinline__ void gemm_phase(PG8_LAS unsigned char* lds, const Gemm g, const Sched& S, const Epi& E) {
;     ...
;             const bool last = (t == nt - 2);
;             const char* a1 = cA + (size_t)(t + 1) * kstep;
;             const char* a2 = last ? nA : cA + (size_t)(t + 2) * kstep; const char* b2 = last ? nB : cB + (size_t)(t + 2) * kstep;
;             const char* a3 = a2 + kstep; const char* b3 = b2 + kstep;
;             if (last && has_next) S.a_ready(nxt);
;             if constexpr (SP2) {
;             PG8_LDB(B0, 0, 0); PG8_LDB(B1, 0, 1); PG8_SCHED; PG8_LDA(At, 0, 0); PG8_STAGE(PG8_SA(1, 1), a1 + hstep, voffA);
;             PG8_WAIT_V(8); PG8_WAIT_L(0); PG8_BAR; PG8_MMA(0, 0, At, B0); PG8_MMA(0, 1, At, B1); PG8_BAR; PG8_SCHED;
;             PG8_LDA(At, 0, 1); PG8_STAGE(PG8_SB(0, 0), b2, voffB); PG8_STAGE(PG8_SB(0, 1), b2 + hstep, voffB); PG8_STAGE(PG8_SA(0, 0), a2, voffA);
;             PG8_WAIT_V(8); PG8_WAIT_L(0); PG8_BAR; PG8_MMA(1, 0, At, B0); PG8_MMA(1, 1, At, B1); PG8_BAR; PG8_SCHED;
.LBB0_136:
	s_add_u32 s18, s58, 0xfffe0080
	s_addc_u32 s19, s59, -1
	s_add_i32 s46, 0, 0x10000
	s_cmp_eq_u32 s79, 4
	s_cselect_b32 s63, s37, s19
	s_cselect_b32 s62, s73, s18
	s_cselect_b32 s19, s11, s78
	s_cselect_b32 s18, s84, s85
	s_add_i32 s76, 0, 0x14000
	v_add_u32_e32 v172, s46, v1
	v_add_u32_e32 v203, s76, v1
	ds_read_b128 v[160:163], v172
	ds_read_b128 v[164:167], v172 offset:1024
	ds_read_b128 v[168:171], v172 offset:2048
	ds_read_b128 v[172:175], v172 offset:3072
	ds_read_b128 v[176:179], v203
	ds_read_b128 v[180:183], v203 offset:1024
	ds_read_b128 v[184:187], v203 offset:2048
	ds_read_b128 v[204:207], v203 offset:3072
	v_lshl_add_u64 v[240:241], s[58:59], 0, v[156:157]
	s_add_i32 m0, s5, 0xc000
	ds_read_b128 v[208:211], v143
	ds_read_b128 v[212:215], v143 offset:1024
	ds_read_b128 v[216:219], v143 offset:2048
	ds_read_b128 v[220:223], v143 offset:3072
	ds_read_b128 v[224:227], v143 offset:4096
	ds_read_b128 v[228:231], v143 offset:5120
	ds_read_b128 v[232:235], v143 offset:6144
	ds_read_b128 v[236:239], v143 offset:7168
	global_load_lds_dwordx4 v[240:241], off
	v_lshl_add_u64 v[240:241], s[58:59], 0, v[158:159]
	s_add_i32 m0, s5, 0xe000
	s_nop 0
	global_load_lds_dwordx4 v[240:241], off
	s_nop 0
	s_setprio 1
	s_waitcnt vmcnt(8)
	s_waitcnt lgkmcnt(0)
	s_barrier
	v_mfma_f32_16x16x32_bf16 v[126:129], v[160:163], v[208:211], v[126:129]
	v_mfma_f32_16x16x32_bf16 v[122:125], v[168:171], v[208:211], v[122:125]
	v_mfma_f32_16x16x32_bf16 v[110:113], v[160:163], v[216:219], v[110:113]
	v_mfma_f32_16x16x32_bf16 v[106:109], v[168:171], v[216:219], v[106:109]
	v_mfma_f32_16x16x32_bf16 v[94:97], v[160:163], v[224:227], v[94:97]
	v_mfma_f32_16x16x32_bf16 v[90:93], v[168:171], v[224:227], v[90:93]
	v_mfma_f32_16x16x32_bf16 v[78:81], v[160:163], v[232:235], v[78:81]
	v_mfma_f32_16x16x32_bf16 v[74:77], v[168:171], v[232:235], v[74:77]
	s_setprio 0
	s_setprio 1
	v_mfma_f32_16x16x32_bf16 v[126:129], v[164:167], v[212:215], v[126:129]
	v_mfma_f32_16x16x32_bf16 v[122:125], v[172:175], v[212:215], v[122:125]
	v_mfma_f32_16x16x32_bf16 v[110:113], v[164:167], v[220:223], v[110:113]
	v_mfma_f32_16x16x32_bf16 v[106:109], v[172:175], v[220:223], v[106:109]
	v_mfma_f32_16x16x32_bf16 v[94:97], v[164:167], v[228:231], v[94:97]
	v_mfma_f32_16x16x32_bf16 v[90:93], v[172:175], v[228:231], v[90:93]
	v_mfma_f32_16x16x32_bf16 v[78:81], v[164:167], v[236:239], v[78:81]
	v_mfma_f32_16x16x32_bf16 v[74:77], v[172:175], v[236:239], v[74:77]
	s_setprio 0
	s_setprio 1
	v_mfma_f32_16x16x32_bf16 v[118:121], v[176:179], v[208:211], v[118:121]
	v_mfma_f32_16x16x32_bf16 v[114:117], v[184:187], v[208:211], v[114:117]
	v_mfma_f32_16x16x32_bf16 v[102:105], v[176:179], v[216:219], v[102:105]
	v_mfma_f32_16x16x32_bf16 v[98:101], v[184:187], v[216:219], v[98:101]
	v_mfma_f32_16x16x32_bf16 v[86:89], v[176:179], v[224:227], v[86:89]
	v_mfma_f32_16x16x32_bf16 v[82:85], v[184:187], v[224:227], v[82:85]
	v_mfma_f32_16x16x32_bf16 v[70:73], v[176:179], v[232:235], v[70:73]
	v_mfma_f32_16x16x32_bf16 v[66:69], v[184:187], v[232:235], v[66:69]
	s_setprio 0
	s_setprio 1
	v_mfma_f32_16x16x32_bf16 v[118:121], v[180:183], v[212:215], v[118:121]
	v_mfma_f32_16x16x32_bf16 v[114:117], v[204:207], v[212:215], v[114:117]
	v_mfma_f32_16x16x32_bf16 v[102:105], v[180:183], v[220:223], v[102:105]
	v_mfma_f32_16x16x32_bf16 v[98:101], v[204:207], v[220:223], v[98:101]
	s_setprio 0
	v_mfma_f32_16x16x32_bf16 v[86:89], v[180:183], v[228:231], v[86:89]
	v_mfma_f32_16x16x32_bf16 v[82:85], v[204:207], v[228:231], v[82:85]
	v_mfma_f32_16x16x32_bf16 v[70:73], v[180:183], v[236:239], v[70:73]
	v_mfma_f32_16x16x32_bf16 v[66:69], v[204:207], v[236:239], v[66:69]
	s_barrier
	s_add_i32 s46, s46, s4
	v_lshl_add_u64 v[240:241], s[18:19], 0, v[148:149]
	s_mov_b32 m0, s46
	ds_read_b128 v[208:211], v143 offset:16384
	ds_read_b128 v[212:215], v143 offset:17408
	ds_read_b128 v[216:219], v143 offset:18432
	ds_read_b128 v[220:223], v143 offset:19456
	ds_read_b128 v[224:227], v143 offset:20480
	ds_read_b128 v[228:231], v143 offset:21504
	ds_read_b128 v[232:235], v143 offset:22528
	ds_read_b128 v[236:239], v143 offset:23552
	global_load_lds_dwordx4 v[240:241], off
	s_add_i32 m0, s46, 0x2000
	s_add_u32 s46, s18, 0x20000
	v_lshl_add_u64 v[242:243], s[18:19], 0, v[144:145]
	s_addc_u32 s47, s19, 0
	s_add_i32 s76, s76, s4
	global_load_lds_dwordx4 v[242:243], off
	v_lshl_add_u64 v[244:245], s[46:47], 0, v[148:149]
	s_mov_b32 m0, s76
	v_lshl_add_u64 v[246:247], s[62:63], 0, v[146:147]
	global_load_lds_dwordx4 v[244:245], off
	v_lshl_add_u64 v[244:245], s[46:47], 0, v[144:145]
	s_add_i32 m0, s76, 0x2000
	s_nop 0
	global_load_lds_dwordx4 v[244:245], off
	v_lshl_add_u64 v[244:245], s[62:63], 0, v[150:151]
	s_mov_b32 m0, s5
	s_nop 0
	global_load_lds_dwordx4 v[244:245], off
	s_mov_b32 m0, s28
	s_nop 0
	global_load_lds_dwordx4 v[246:247], off
	s_setprio 1
	s_waitcnt vmcnt(8)
	s_waitcnt lgkmcnt(0)
	s_barrier
; #define PG8_STAGE(bufoff, gbase, voff) do { _Pragma("unroll") for (int _i = 0; _i < 2; ++_i) \
;         __builtin_amdgcn_global_load_lds((const unsigned*)((const char*)(gbase) + (voff)[_i]), (PG8_LAS unsigned*)(lds + (bufoff) + ldsw + _i * 8192), 16, 0, 0); } while (0)
; #define PG8_LDA(dst, b, h) do { _Pragma("unroll") for (int m = 0; m < 4; ++m) _Pragma("unroll") for (int k = 0; k < 2; ++k) dst[m][k] = *(const PG8_LAS bf16x8*)(lds + PG8_SA(b, h) + aoff + m * 2048 + k * 1024); } while (0)
; #define PG8_LDB(dst, b, h) do { _Pragma("unroll") for (int n = 0; n < 2; ++n) _Pragma("unroll") for (int k = 0; k < 2; ++k) dst[n][k] = *(const PG8_LAS bf16x8*)(lds + PG8_SB(b, h) + boff + n * 2048 + k * 1024); } while (0)
; #define PG8_MMA(ai, bj, At, Bt) do { __builtin_amdgcn_s_setprio(1); _Pragma("unroll") for (int m = 0; m < 4; ++m) _Pragma("unroll") for (int n = 0; n < 2; ++n) _Pragma("unroll") for (int k = 0; k < 2; ++k) \
;         acc[ai][bj][m][n] = __builtin_amdgcn_mfma_f32_16x16x32_bf16(Bt[n][k], At[m][k], acc[ai][bj][m][n], 0, 0, 0); __builtin_amdgcn_s_setprio(0); } while (0)
; #define PG8_WAIT_V(n) asm volatile("s_waitcnt vmcnt(" #n ")" ::: "memory")
; #define PG8_WAIT_L(n) asm volatile("s_waitcnt lgkmcnt(" #n ")" ::: "memory")
; #define PG8_BAR __builtin_amdgcn_s_barrier()
; #define PG8_SCHED __builtin_amdgcn_sched_barrier(0)
; template <class Epi, class Sched, bool ALIGN_EPI = false, bool SP2 = false>
; __device__ __forceinline__ void gemm_phase(PG8_LAS unsigned char* lds, const Gemm g, const Sched& S, const Epi& E) {
;     ...
;             PG8_WAIT_V(8); PG8_WAIT_L(0); PG8_BAR; PG8_MMA(1, 0, At, B0); PG8_MMA(1, 1, At, B1); PG8_BAR; PG8_SCHED;
;             PG8_LDB(B0, 1, 0); PG8_LDB(B1, 1, 1); PG8_SCHED; PG8_LDA(At, 1, 0); PG8_STAGE(PG8_SA(0, 1), a2 + hstep, voffA);
;             PG8_WAIT_V(8); PG8_WAIT_L(0); PG8_BAR; PG8_MMA(0, 0, At, B0); PG8_MMA(0, 1, At, B1); PG8_BAR; PG8_SCHED;
	v_mfma_f32_16x16x32_bf16 v[62:65], v[160:163], v[208:211], v[62:65]
	v_mfma_f32_16x16x32_bf16 v[58:61], v[168:171], v[208:211], v[58:61]
	v_mfma_f32_16x16x32_bf16 v[46:49], v[160:163], v[216:219], v[46:49]
	v_mfma_f32_16x16x32_bf16 v[42:45], v[168:171], v[216:219], v[42:45]
	v_mfma_f32_16x16x32_bf16 v[30:33], v[160:163], v[224:227], v[30:33]
	v_mfma_f32_16x16x32_bf16 v[26:29], v[168:171], v[224:227], v[26:29]
	v_mfma_f32_16x16x32_bf16 v[14:17], v[160:163], v[232:235], v[14:17]
	v_mfma_f32_16x16x32_bf16 v[10:13], v[168:171], v[232:235], v[10:13]
	s_setprio 0
	s_setprio 1
	v_mfma_f32_16x16x32_bf16 v[62:65], v[164:167], v[212:215], v[62:65]
	v_mfma_f32_16x16x32_bf16 v[58:61], v[172:175], v[212:215], v[58:61]
	v_mfma_f32_16x16x32_bf16 v[46:49], v[164:167], v[220:223], v[46:49]
	v_mfma_f32_16x16x32_bf16 v[42:45], v[172:175], v[220:223], v[42:45]
	v_mfma_f32_16x16x32_bf16 v[30:33], v[164:167], v[228:231], v[30:33]
	v_mfma_f32_16x16x32_bf16 v[26:29], v[172:175], v[228:231], v[26:29]
	v_mfma_f32_16x16x32_bf16 v[14:17], v[164:167], v[236:239], v[14:17]
	v_mfma_f32_16x16x32_bf16 v[10:13], v[172:175], v[236:239], v[10:13]
	s_setprio 0
	s_setprio 1
	v_mfma_f32_16x16x32_bf16 v[54:57], v[176:179], v[208:211], v[54:57]
	v_mfma_f32_16x16x32_bf16 v[50:53], v[184:187], v[208:211], v[50:53]
	v_mfma_f32_16x16x32_bf16 v[38:41], v[176:179], v[216:219], v[38:41]
	v_mfma_f32_16x16x32_bf16 v[34:37], v[184:187], v[216:219], v[34:37]
	v_mfma_f32_16x16x32_bf16 v[22:25], v[176:179], v[224:227], v[22:25]
	v_mfma_f32_16x16x32_bf16 v[18:21], v[184:187], v[224:227], v[18:21]
	v_mfma_f32_16x16x32_bf16 v[6:9], v[176:179], v[232:235], v[6:9]
	v_mfma_f32_16x16x32_bf16 v[2:5], v[184:187], v[232:235], v[2:5]
	s_setprio 0
	s_setprio 1
	v_mfma_f32_16x16x32_bf16 v[54:57], v[180:183], v[212:215], v[54:57]
	v_mfma_f32_16x16x32_bf16 v[50:53], v[204:207], v[212:215], v[50:53]
	v_mfma_f32_16x16x32_bf16 v[38:41], v[180:183], v[220:223], v[38:41]
	v_mfma_f32_16x16x32_bf16 v[34:37], v[204:207], v[220:223], v[34:37]
	s_setprio 0
	v_mfma_f32_16x16x32_bf16 v[22:25], v[180:183], v[228:231], v[22:25]
	v_mfma_f32_16x16x32_bf16 v[18:21], v[204:207], v[228:231], v[18:21]
	v_mfma_f32_16x16x32_bf16 v[6:9], v[180:183], v[236:239], v[6:9]
	v_mfma_f32_16x16x32_bf16 v[2:5], v[204:207], v[236:239], v[2:5]
	s_barrier
	s_add_i32 s76, 0, 0x18000
	s_add_i32 s77, 0, 0x1c000
	v_add_u32_e32 v172, s76, v1
	v_add_u32_e32 v203, s77, v1
	ds_read_b128 v[160:163], v172
	ds_read_b128 v[164:167], v172 offset:1024
	ds_read_b128 v[168:171], v172 offset:2048
	ds_read_b128 v[172:175], v172 offset:3072
	ds_read_b128 v[176:179], v203
	ds_read_b128 v[180:183], v203 offset:1024
	ds_read_b128 v[184:187], v203 offset:2048
	ds_read_b128 v[204:207], v203 offset:3072
	s_add_u32 s46, s62, 0x20000
	s_addc_u32 s47, s63, 0
	s_mov_b32 m0, s30
	v_lshl_add_u64 v[248:249], s[46:47], 0, v[150:151]
	ds_read_b128 v[208:211], v143 offset:32768
	ds_read_b128 v[212:215], v143 offset:33792
	ds_read_b128 v[216:219], v143 offset:34816
	ds_read_b128 v[220:223], v143 offset:35840
	ds_read_b128 v[224:227], v143 offset:36864
	ds_read_b128 v[228:231], v143 offset:37888
	ds_read_b128 v[232:235], v143 offset:38912
	ds_read_b128 v[236:239], v143 offset:39936
	global_load_lds_dwordx4 v[248:249], off
	v_lshl_add_u64 v[248:249], s[46:47], 0, v[146:147]
	s_mov_b32 m0, s34
	s_nop 0
	global_load_lds_dwordx4 v[248:249], off
	s_setprio 1
	s_waitcnt vmcnt(8)
	s_waitcnt lgkmcnt(0)
	s_barrier
	v_mfma_f32_16x16x32_bf16 v[126:129], v[160:163], v[208:211], v[126:129]
	v_mfma_f32_16x16x32_bf16 v[122:125], v[168:171], v[208:211], v[122:125]
	v_mfma_f32_16x16x32_bf16 v[110:113], v[160:163], v[216:219], v[110:113]
	v_mfma_f32_16x16x32_bf16 v[106:109], v[168:171], v[216:219], v[106:109]
	v_mfma_f32_16x16x32_bf16 v[94:97], v[160:163], v[224:227], v[94:97]
	v_mfma_f32_16x16x32_bf16 v[90:93], v[168:171], v[224:227], v[90:93]
	v_mfma_f32_16x16x32_bf16 v[78:81], v[160:163], v[232:235], v[78:81]
	v_mfma_f32_16x16x32_bf16 v[74:77], v[168:171], v[232:235], v[74:77]
	s_setprio 0
	s_setprio 1
	v_mfma_f32_16x16x32_bf16 v[126:129], v[164:167], v[212:215], v[126:129]
	v_mfma_f32_16x16x32_bf16 v[122:125], v[172:175], v[212:215], v[122:125]
	v_mfma_f32_16x16x32_bf16 v[110:113], v[164:167], v[220:223], v[110:113]
	v_mfma_f32_16x16x32_bf16 v[106:109], v[172:175], v[220:223], v[106:109]
	v_mfma_f32_16x16x32_bf16 v[94:97], v[164:167], v[228:231], v[94:97]
	v_mfma_f32_16x16x32_bf16 v[90:93], v[172:175], v[228:231], v[90:93]
	v_mfma_f32_16x16x32_bf16 v[78:81], v[164:167], v[236:239], v[78:81]
	v_mfma_f32_16x16x32_bf16 v[74:77], v[172:175], v[236:239], v[74:77]
	s_setprio 0
	s_setprio 1
	v_mfma_f32_16x16x32_bf16 v[118:121], v[176:179], v[208:211], v[118:121]
	v_mfma_f32_16x16x32_bf16 v[114:117], v[184:187], v[208:211], v[114:117]
	v_mfma_f32_16x16x32_bf16 v[102:105], v[176:179], v[216:219], v[102:105]
	v_mfma_f32_16x16x32_bf16 v[98:101], v[184:187], v[216:219], v[98:101]
	v_mfma_f32_16x16x32_bf16 v[86:89], v[176:179], v[224:227], v[86:89]
	v_mfma_f32_16x16x32_bf16 v[82:85], v[184:187], v[224:227], v[82:85]
	v_mfma_f32_16x16x32_bf16 v[70:73], v[176:179], v[232:235], v[70:73]
	v_mfma_f32_16x16x32_bf16 v[66:69], v[184:187], v[232:235], v[66:69]
	s_setprio 0
	s_setprio 1
	v_mfma_f32_16x16x32_bf16 v[118:121], v[180:183], v[212:215], v[118:121]
	v_mfma_f32_16x16x32_bf16 v[114:117], v[204:207], v[212:215], v[114:117]
	v_mfma_f32_16x16x32_bf16 v[102:105], v[180:183], v[220:223], v[102:105]
	v_mfma_f32_16x16x32_bf16 v[98:101], v[204:207], v[220:223], v[98:101]
	s_setprio 0
	v_mfma_f32_16x16x32_bf16 v[86:89], v[180:183], v[228:231], v[86:89]
	v_mfma_f32_16x16x32_bf16 v[82:85], v[204:207], v[228:231], v[82:85]
	v_mfma_f32_16x16x32_bf16 v[70:73], v[180:183], v[236:239], v[70:73]
	v_mfma_f32_16x16x32_bf16 v[66:69], v[204:207], v[236:239], v[66:69]
	s_barrier
; #define PG8_STAGE(bufoff, gbase, voff) do { _Pragma("unroll") for (int _i = 0; _i < 2; ++_i) \
;         __builtin_amdgcn_global_load_lds((const unsigned*)((const char*)(gbase) + (voff)[_i]), (PG8_LAS unsigned*)(lds + (bufoff) + ldsw + _i * 8192), 16, 0, 0); } while (0)
; #define PG8_LDA(dst, b, h) do { _Pragma("unroll") for (int m = 0; m < 4; ++m) _Pragma("unroll") for (int k = 0; k < 2; ++k) dst[m][k] = *(const PG8_LAS bf16x8*)(lds + PG8_SA(b, h) + aoff + m * 2048 + k * 1024); } while (0)
; #define PG8_MMA(ai, bj, At, Bt) do { __builtin_amdgcn_s_setprio(1); _Pragma("unroll") for (int m = 0; m < 4; ++m) _Pragma("unroll") for (int n = 0; n < 2; ++n) _Pragma("unroll") for (int k = 0; k < 2; ++k) \
;         acc[ai][bj][m][n] = __builtin_amdgcn_mfma_f32_16x16x32_bf16(Bt[n][k], At[m][k], acc[ai][bj][m][n], 0, 0, 0); __builtin_amdgcn_s_setprio(0); } while (0)
; #define PG8_WAIT_V(n) asm volatile("s_waitcnt vmcnt(" #n ")" ::: "memory")
; #define PG8_WAIT_L(n) asm volatile("s_waitcnt lgkmcnt(" #n ")" ::: "memory")
; #define PG8_BAR __builtin_amdgcn_s_barrier()
; #define PG8_SCHED __builtin_amdgcn_sched_barrier(0)
;     __device__ __forceinline__ void operator()(const f32x4 (&acc)[2][2][4][2], const Unit& u, int wr, int wc, int fr, int fq) const {
;         const int row0 = u.pm * BM + wr * 64 + fr, col0 = u.pn * BM + wc * 32 + 8 * fq;
;         const int tidn = (wr * 4 + wc) * 64 + fq * 16 + fr;
;         const u32x4* gp = (const u32x4*)G8 + (size_t)(u.pm * 16 + gsel + u.pn) * 8 * 512 + tidn;
;         u32x4* mp = M1 + (size_t)(u.pm * 8 + u.pn) * 16 * 512 + tidn;
;         constexpr float K255 = 1.0f / 255.0f;
; #pragma unroll
;         for (int ai = 0; ai < 2; ++ai)
; #pragma unroll
;             for (int m = 0; m < 4; ++m) { const size_t row = (size_t)(row0 + ai * HALF + m * 16);
;                 const u32x4 gw = gp[(ai * 4 + m) * 512];
; template <class Epi, class Sched, bool ALIGN_EPI = false, bool SP2 = false>
; __device__ __forceinline__ void gemm_phase(PG8_LAS unsigned char* lds, const Gemm g, const Sched& S, const Epi& E) {
;     ...
;             PG8_LDA(At, 1, 1); PG8_STAGE(PG8_SB(1, 0), b3, voffB); PG8_STAGE(PG8_SB(1, 1), b3 + hstep, voffB); PG8_STAGE(PG8_SA(1, 0), a3, voffA);
;             PG8_WAIT_V(8); PG8_WAIT_L(0); PG8_BAR; PG8_MMA(1, 0, At, B0); PG8_MMA(1, 1, At, B1); PG8_BAR; PG8_SCHED;
	s_add_i32 s46, s76, s4
	v_lshl_add_u64 v[240:241], v[240:241], 0, s[68:69]
	s_mov_b32 m0, s46
	ds_read_b128 v[208:211], v143 offset:49152
	ds_read_b128 v[212:215], v143 offset:50176
	ds_read_b128 v[216:219], v143 offset:51200
	ds_read_b128 v[220:223], v143 offset:52224
	ds_read_b128 v[224:227], v143 offset:53248
	ds_read_b128 v[228:231], v143 offset:54272
	ds_read_b128 v[232:235], v143 offset:55296
	ds_read_b128 v[236:239], v143 offset:56320
	global_load_lds_dwordx4 v[240:241], off
	s_add_i32 m0, s46, 0x2000
	s_add_u32 s18, s18, 0x20080
	v_lshl_add_u64 v[240:241], v[242:243], 0, s[68:69]
	s_addc_u32 s19, s19, 0
	s_add_i32 s46, s77, s4
	global_load_lds_dwordx4 v[240:241], off
	v_lshl_add_u64 v[240:241], s[18:19], 0, v[148:149]
	s_mov_b32 m0, s46
	s_nop 0
	global_load_lds_dwordx4 v[240:241], off
	v_lshl_add_u64 v[240:241], s[18:19], 0, v[144:145]
	s_add_i32 m0, s46, 0x2000
	s_nop 0
	global_load_lds_dwordx4 v[240:241], off
	v_lshl_add_u64 v[240:241], v[244:245], 0, s[68:69]
	s_mov_b32 m0, s54
	s_nop 0
	global_load_lds_dwordx4 v[240:241], off
	v_lshl_add_u64 v[240:241], v[246:247], 0, s[68:69]
	s_mov_b32 m0, s57
	s_nop 0
	global_load_lds_dwordx4 v[240:241], off
	s_nop 0
	s_setprio 1
	s_waitcnt vmcnt(8)
	s_waitcnt lgkmcnt(0)
	s_barrier
	v_mfma_f32_16x16x32_bf16 v[62:65], v[160:163], v[208:211], v[62:65]
	v_mfma_f32_16x16x32_bf16 v[58:61], v[168:171], v[208:211], v[58:61]
	v_mfma_f32_16x16x32_bf16 v[46:49], v[160:163], v[216:219], v[46:49]
	v_mfma_f32_16x16x32_bf16 v[42:45], v[168:171], v[216:219], v[42:45]
	v_mfma_f32_16x16x32_bf16 v[30:33], v[160:163], v[224:227], v[30:33]
	v_mfma_f32_16x16x32_bf16 v[26:29], v[168:171], v[224:227], v[26:29]
	v_mfma_f32_16x16x32_bf16 v[14:17], v[160:163], v[232:235], v[14:17]
	v_mfma_f32_16x16x32_bf16 v[10:13], v[168:171], v[232:235], v[10:13]
	s_setprio 0
	s_setprio 1
	v_mfma_f32_16x16x32_bf16 v[62:65], v[164:167], v[212:215], v[62:65]
	v_mfma_f32_16x16x32_bf16 v[58:61], v[172:175], v[212:215], v[58:61]
	v_mfma_f32_16x16x32_bf16 v[46:49], v[164:167], v[220:223], v[46:49]
	v_mfma_f32_16x16x32_bf16 v[42:45], v[172:175], v[220:223], v[42:45]
	v_mfma_f32_16x16x32_bf16 v[30:33], v[164:167], v[228:231], v[30:33]
	v_mfma_f32_16x16x32_bf16 v[26:29], v[172:175], v[228:231], v[26:29]
	v_mfma_f32_16x16x32_bf16 v[14:17], v[164:167], v[236:239], v[14:17]
	v_mfma_f32_16x16x32_bf16 v[10:13], v[172:175], v[236:239], v[10:13]
	s_setprio 0
	s_setprio 1
	v_mfma_f32_16x16x32_bf16 v[54:57], v[176:179], v[208:211], v[54:57]
	v_mfma_f32_16x16x32_bf16 v[50:53], v[184:187], v[208:211], v[50:53]
	v_mfma_f32_16x16x32_bf16 v[38:41], v[176:179], v[216:219], v[38:41]
	v_mfma_f32_16x16x32_bf16 v[34:37], v[184:187], v[216:219], v[34:37]
	v_mfma_f32_16x16x32_bf16 v[22:25], v[176:179], v[224:227], v[22:25]
	v_mfma_f32_16x16x32_bf16 v[18:21], v[184:187], v[224:227], v[18:21]
	v_mfma_f32_16x16x32_bf16 v[6:9], v[176:179], v[232:235], v[6:9]
	v_mfma_f32_16x16x32_bf16 v[2:5], v[184:187], v[232:235], v[2:5]
	s_setprio 0
	s_setprio 1
	v_mfma_f32_16x16x32_bf16 v[54:57], v[180:183], v[212:215], v[54:57]
	v_mfma_f32_16x16x32_bf16 v[50:53], v[204:207], v[212:215], v[50:53]
	v_mfma_f32_16x16x32_bf16 v[38:41], v[180:183], v[220:223], v[38:41]
	v_mfma_f32_16x16x32_bf16 v[34:37], v[204:207], v[220:223], v[34:37]
	s_setprio 0
	v_mfma_f32_16x16x32_bf16 v[22:25], v[180:183], v[228:231], v[22:25]
	v_mfma_f32_16x16x32_bf16 v[18:21], v[204:207], v[228:231], v[18:21]
	v_mfma_f32_16x16x32_bf16 v[6:9], v[180:183], v[236:239], v[6:9]
	v_mfma_f32_16x16x32_bf16 v[2:5], v[204:207], v[236:239], v[2:5]
	s_barrier
	s_add_i32 s79, s79, 2
	s_add_u32 s58, s58, 0x100
	s_addc_u32 s59, s59, 0
	s_add_u32 s85, s85, 0x100
	s_addc_u32 s78, s78, 0
	s_cmp_gt_u32 s79, 5
	s_cbranch_scc0 .LBB0_136
	s_lshl_b32 s11, s67, 4
	s_add_i32 s18, s11, s86
	s_ashr_i32 s19, s18, 31
	s_lshl_b64 s[46:47], s[18:19], 16
	v_lshl_add_u64 v[162:163], v[152:153], 0, s[46:47]
	s_lshl_b32 s11, s67, 3
	s_sub_i32 s18, s18, s11
	s_ashr_i32 s19, s18, 31
	s_lshl_b64 s[18:19], s[18:19], 17
	v_lshl_add_u64 v[160:161], v[154:155], 0, s[18:19]
	s_mov_b32 s47, 0
	global_load_dwordx4 v[168:171], v[162:163], off
	s_mov_b32 s46, 0x2000
	v_lshl_add_u64 v[164:165], v[162:163], 0, s[46:47]
	global_load_dwordx4 v[172:175], v[164:165], off
	s_mov_b32 s46, 0x4000
	v_lshl_add_u64 v[164:165], v[162:163], 0, s[46:47]
	global_load_dwordx4 v[176:179], v[164:165], off
	s_mov_b32 s46, 0x6000
	v_lshl_add_u64 v[164:165], v[162:163], 0, s[46:47]
	global_load_dwordx4 v[180:183], v[164:165], off
	s_mov_b32 s46, 0x8000
	v_lshl_add_u64 v[164:165], v[162:163], 0, s[46:47]
	global_load_dwordx4 v[184:187], v[164:165], off
	s_mov_b32 s46, 0xa000
	v_lshl_add_u64 v[164:165], v[162:163], 0, s[46:47]
	global_load_dwordx4 v[204:207], v[164:165], off
	s_mov_b32 s46, 0xc000
	v_lshl_add_u64 v[164:165], v[162:163], 0, s[46:47]
	global_load_dwordx4 v[208:211], v[164:165], off
	s_mov_b32 s46, 0xe000
	v_lshl_add_u64 v[164:165], v[162:163], 0, s[46:47]
	global_load_dwordx4 v[212:215], v[164:165], off
	s_and_b64 vcc, exec, s[8:9]
	s_cbranch_vccz .Lg0_nobar
	s_barrier

; #define PG8_STAGE(bufoff, gbase, voff) do { _Pragma("unroll") for (int _i = 0; _i < 2; ++_i) \
;         __builtin_amdgcn_global_load_lds((const unsigned*)((const char*)(gbase) + (voff)[_i]), (PG8_LAS unsigned*)(lds + (bufoff) + ldsw + _i * 8192), 16, 0, 0); } while (0)
; #define PG8_LDA(dst, b, h) do { _Pragma("unroll") for (int m = 0; m < 4; ++m) _Pragma("unroll") for (int k = 0; k < 2; ++k) dst[m][k] = *(const PG8_LAS bf16x8*)(lds + PG8_SA(b, h) + aoff + m * 2048 + k * 1024); } while (0)
; #define PG8_LDB(dst, b, h) do { _Pragma("unroll") for (int n = 0; n < 2; ++n) _Pragma("unroll") for (int k = 0; k < 2; ++k) dst[n][k] = *(const PG8_LAS bf16x8*)(lds + PG8_SB(b, h) + boff + n * 2048 + k * 1024); } while (0)
; #define PG8_MMA(ai, bj, At, Bt) do { __builtin_amdgcn_s_setprio(1); _Pragma("unroll") for (int m = 0; m < 4; ++m) _Pragma("unroll") for (int n = 0; n < 2; ++n) _Pragma("unroll") for (int k = 0; k < 2; ++k) \
;         acc[ai][bj][m][n] = __builtin_amdgcn_mfma_f32_16x16x32_bf16(Bt[n][k], At[m][k], acc[ai][bj][m][n], 0, 0, 0); __builtin_amdgcn_s_setprio(0); } while (0)
; #define PG8_WAIT_V(n) asm volatile("s_waitcnt vmcnt(" #n ")" ::: "memory")
; #define PG8_WAIT_L(n) asm volatile("s_waitcnt lgkmcnt(" #n ")" ::: "memory")
; template <class Epi, class Sched, bool ALIGN_EPI = false, bool SP2 = false>
; __device__ __forceinline__ void gemm_phase(PG8_LAS unsigned char* lds, const Gemm g, const Sched& S, const Epi& E) {
;     ...
;             const bool last = (t == nt - 2);
;             const char* a1 = cA + (size_t)(t + 1) * kstep;
;             const char* a2 = last ? nA : cA + (size_t)(t + 2) * kstep; const char* b2 = last ? nB : cB + (size_t)(t + 2) * kstep;
;             const char* a3 = a2 + kstep; const char* b3 = b2 + kstep;
;             if (last && has_next) S.a_ready(nxt);
;             if constexpr (SP2) {
;             PG8_LDB(B0, 0, 0); PG8_LDB(B1, 0, 1); PG8_SCHED; PG8_LDA(At, 0, 0); PG8_STAGE(PG8_SA(1, 1), a1 + hstep, voffA);
;             PG8_WAIT_V(8); PG8_WAIT_L(0); PG8_BAR; PG8_MMA(0, 0, At, B0); PG8_MMA(0, 1, At, B1); PG8_BAR; PG8_SCHED;
;             PG8_LDA(At, 0, 1); PG8_STAGE(PG8_SB(0, 0), b2, voffB); PG8_STAGE(PG8_SB(0, 1), b2 + hstep, voffB); PG8_STAGE(PG8_SA(0, 0), a2, voffA);
;             PG8_WAIT_V(8); PG8_WAIT_L(0); PG8_BAR; PG8_MMA(1, 0, At, B0); PG8_MMA(1, 1, At, B1); PG8_BAR; PG8_SCHED;
.LBB0_160:
	s_add_u32 s42, s36, 0x100
	s_addc_u32 s43, s37, 0
	s_add_i32 s47, 0, 0x10000
	s_cmp_eq_u32 s46, 20
	s_cselect_b32 s45, s1, s43
	s_cselect_b32 s44, s0, s42
	s_cselect_b32 s19, s7, s73
	s_cselect_b32 s18, s6, s60
	s_add_i32 s76, 0, 0x14000
	v_add_u32_e32 v174, s47, v143
	v_add_u32_e32 v186, s76, v143
	ds_read_b128 v[160:163], v174
	ds_read_b128 v[164:167], v174 offset:1024
	ds_read_b128 v[170:173], v174 offset:2048
	ds_read_b128 v[174:177], v174 offset:3072
	ds_read_b128 v[178:181], v186
	ds_read_b128 v[182:185], v186 offset:1024
	ds_read_b128 v[204:207], v186 offset:2048
	ds_read_b128 v[208:211], v186 offset:3072
	v_lshl_add_u64 v[186:187], s[36:37], 0, v[156:157]
	s_add_i32 m0, s54, 0xc000
	ds_read_b128 v[212:215], v169
	ds_read_b128 v[216:219], v169 offset:1024
	ds_read_b128 v[220:223], v169 offset:2048
	ds_read_b128 v[224:227], v169 offset:3072
	ds_read_b128 v[228:231], v169 offset:4096
	ds_read_b128 v[232:235], v169 offset:5120
	ds_read_b128 v[236:239], v169 offset:6144
	ds_read_b128 v[240:243], v169 offset:7168
	global_load_lds_dwordx4 v[186:187], off
	v_lshl_add_u64 v[186:187], s[36:37], 0, v[158:159]
	s_add_i32 m0, s54, 0xe000
	s_nop 0
	global_load_lds_dwordx4 v[186:187], off
	s_setprio 1
	s_waitcnt vmcnt(8)
	s_waitcnt lgkmcnt(0)
	s_barrier
	v_mfma_f32_16x16x32_bf16 v[126:129], v[160:163], v[212:215], v[126:129]
	v_mfma_f32_16x16x32_bf16 v[122:125], v[170:173], v[212:215], v[122:125]
	v_mfma_f32_16x16x32_bf16 v[110:113], v[160:163], v[220:223], v[110:113]
	v_mfma_f32_16x16x32_bf16 v[106:109], v[170:173], v[220:223], v[106:109]
	v_mfma_f32_16x16x32_bf16 v[94:97], v[160:163], v[228:231], v[94:97]
	v_mfma_f32_16x16x32_bf16 v[90:93], v[170:173], v[228:231], v[90:93]
	v_mfma_f32_16x16x32_bf16 v[78:81], v[160:163], v[236:239], v[78:81]
	v_mfma_f32_16x16x32_bf16 v[74:77], v[170:173], v[236:239], v[74:77]
	s_setprio 0
	s_setprio 1
	v_mfma_f32_16x16x32_bf16 v[126:129], v[164:167], v[216:219], v[126:129]
	v_mfma_f32_16x16x32_bf16 v[122:125], v[174:177], v[216:219], v[122:125]
	v_mfma_f32_16x16x32_bf16 v[110:113], v[164:167], v[224:227], v[110:113]
	v_mfma_f32_16x16x32_bf16 v[106:109], v[174:177], v[224:227], v[106:109]
	v_mfma_f32_16x16x32_bf16 v[94:97], v[164:167], v[232:235], v[94:97]
	v_mfma_f32_16x16x32_bf16 v[90:93], v[174:177], v[232:235], v[90:93]
	v_mfma_f32_16x16x32_bf16 v[78:81], v[164:167], v[240:243], v[78:81]
	v_mfma_f32_16x16x32_bf16 v[74:77], v[174:177], v[240:243], v[74:77]
	s_setprio 0
	s_setprio 1
	v_mfma_f32_16x16x32_bf16 v[118:121], v[178:181], v[212:215], v[118:121]
	v_mfma_f32_16x16x32_bf16 v[114:117], v[204:207], v[212:215], v[114:117]
	v_mfma_f32_16x16x32_bf16 v[102:105], v[178:181], v[220:223], v[102:105]
	v_mfma_f32_16x16x32_bf16 v[98:101], v[204:207], v[220:223], v[98:101]
	v_mfma_f32_16x16x32_bf16 v[86:89], v[178:181], v[228:231], v[86:89]
	v_mfma_f32_16x16x32_bf16 v[82:85], v[204:207], v[228:231], v[82:85]
	v_mfma_f32_16x16x32_bf16 v[70:73], v[178:181], v[236:239], v[70:73]
	v_mfma_f32_16x16x32_bf16 v[66:69], v[204:207], v[236:239], v[66:69]
	s_setprio 0
	s_setprio 1
	v_mfma_f32_16x16x32_bf16 v[118:121], v[182:185], v[216:219], v[118:121]
	v_mfma_f32_16x16x32_bf16 v[114:117], v[208:211], v[216:219], v[114:117]
	v_mfma_f32_16x16x32_bf16 v[102:105], v[182:185], v[224:227], v[102:105]
	v_mfma_f32_16x16x32_bf16 v[98:101], v[208:211], v[224:227], v[98:101]
	s_setprio 0
	v_mfma_f32_16x16x32_bf16 v[86:89], v[182:185], v[232:235], v[86:89]
	v_mfma_f32_16x16x32_bf16 v[82:85], v[208:211], v[232:235], v[82:85]
	v_mfma_f32_16x16x32_bf16 v[70:73], v[182:185], v[240:243], v[70:73]
	v_mfma_f32_16x16x32_bf16 v[66:69], v[208:211], v[240:243], v[66:69]
	s_barrier
	s_add_i32 s36, s47, s4
	v_lshl_add_u64 v[186:187], s[18:19], 0, v[148:149]
	s_mov_b32 m0, s36
	ds_read_b128 v[212:215], v169 offset:16384
	ds_read_b128 v[216:219], v169 offset:17408
	ds_read_b128 v[220:223], v169 offset:18432
	ds_read_b128 v[224:227], v169 offset:19456
	ds_read_b128 v[228:231], v169 offset:20480
	ds_read_b128 v[232:235], v169 offset:21504
	ds_read_b128 v[236:239], v169 offset:22528
	ds_read_b128 v[240:243], v169 offset:23552
	global_load_lds_dwordx4 v[186:187], off
	s_add_i32 m0, s36, 0x2000
	s_add_u32 s36, s18, 0x60000
	v_lshl_add_u64 v[244:245], s[18:19], 0, v[144:145]
	s_addc_u32 s37, s19, 0
	s_add_i32 s47, s76, s4
	global_load_lds_dwordx4 v[244:245], off
	v_lshl_add_u64 v[246:247], s[36:37], 0, v[148:149]
	s_mov_b32 m0, s47
	v_lshl_add_u64 v[248:249], s[44:45], 0, v[146:147]
	global_load_lds_dwordx4 v[246:247], off
	v_lshl_add_u64 v[246:247], s[36:37], 0, v[144:145]
	s_add_i32 m0, s47, 0x2000
	s_nop 0
	global_load_lds_dwordx4 v[246:247], off
	v_lshl_add_u64 v[246:247], s[44:45], 0, v[150:151]
	s_mov_b32 m0, s54
	s_nop 0
	global_load_lds_dwordx4 v[246:247], off
	s_mov_b32 m0, s57
	s_nop 0
	global_load_lds_dwordx4 v[248:249], off
	s_setprio 1
	s_waitcnt vmcnt(8)
	s_waitcnt lgkmcnt(0)
	s_barrier
; #define PG8_STAGE(bufoff, gbase, voff) do { _Pragma("unroll") for (int _i = 0; _i < 2; ++_i) \
;         __builtin_amdgcn_global_load_lds((const unsigned*)((const char*)(gbase) + (voff)[_i]), (PG8_LAS unsigned*)(lds + (bufoff) + ldsw + _i * 8192), 16, 0, 0); } while (0)
; #define PG8_LDA(dst, b, h) do { _Pragma("unroll") for (int m = 0; m < 4; ++m) _Pragma("unroll") for (int k = 0; k < 2; ++k) dst[m][k] = *(const PG8_LAS bf16x8*)(lds + PG8_SA(b, h) + aoff + m * 2048 + k * 1024); } while (0)
; #define PG8_LDB(dst, b, h) do { _Pragma("unroll") for (int n = 0; n < 2; ++n) _Pragma("unroll") for (int k = 0; k < 2; ++k) dst[n][k] = *(const PG8_LAS bf16x8*)(lds + PG8_SB(b, h) + boff + n * 2048 + k * 1024); } while (0)
; #define PG8_MMA(ai, bj, At, Bt) do { __builtin_amdgcn_s_setprio(1); _Pragma("unroll") for (int m = 0; m < 4; ++m) _Pragma("unroll") for (int n = 0; n < 2; ++n) _Pragma("unroll") for (int k = 0; k < 2; ++k) \
;         acc[ai][bj][m][n] = __builtin_amdgcn_mfma_f32_16x16x32_bf16(Bt[n][k], At[m][k], acc[ai][bj][m][n], 0, 0, 0); __builtin_amdgcn_s_setprio(0); } while (0)
; #define PG8_WAIT_V(n) asm volatile("s_waitcnt vmcnt(" #n ")" ::: "memory")
; #define PG8_WAIT_L(n) asm volatile("s_waitcnt lgkmcnt(" #n ")" ::: "memory")
; #define PG8_BAR __builtin_amdgcn_s_barrier()
; #define PG8_SCHED __builtin_amdgcn_sched_barrier(0)
; template <class Epi, class Sched, bool ALIGN_EPI = false, bool SP2 = false>
; __device__ __forceinline__ void gemm_phase(PG8_LAS unsigned char* lds, const Gemm g, const Sched& S, const Epi& E) {
;     ...
;             PG8_WAIT_V(8); PG8_WAIT_L(0); PG8_BAR; PG8_MMA(1, 0, At, B0); PG8_MMA(1, 1, At, B1); PG8_BAR; PG8_SCHED;
;             PG8_LDB(B0, 1, 0); PG8_LDB(B1, 1, 1); PG8_SCHED; PG8_LDA(At, 1, 0); PG8_STAGE(PG8_SA(0, 1), a2 + hstep, voffA);
;             PG8_WAIT_V(8); PG8_WAIT_L(0); PG8_BAR; PG8_MMA(0, 0, At, B0); PG8_MMA(0, 1, At, B1); PG8_BAR; PG8_SCHED;
	v_mfma_f32_16x16x32_bf16 v[62:65], v[160:163], v[212:215], v[62:65]
	v_mfma_f32_16x16x32_bf16 v[58:61], v[170:173], v[212:215], v[58:61]
	v_mfma_f32_16x16x32_bf16 v[46:49], v[160:163], v[220:223], v[46:49]
	v_mfma_f32_16x16x32_bf16 v[42:45], v[170:173], v[220:223], v[42:45]
	v_mfma_f32_16x16x32_bf16 v[30:33], v[160:163], v[228:231], v[30:33]
	v_mfma_f32_16x16x32_bf16 v[26:29], v[170:173], v[228:231], v[26:29]
	v_mfma_f32_16x16x32_bf16 v[14:17], v[160:163], v[236:239], v[14:17]
	v_mfma_f32_16x16x32_bf16 v[10:13], v[170:173], v[236:239], v[10:13]
	s_setprio 0
	s_setprio 1
	v_mfma_f32_16x16x32_bf16 v[62:65], v[164:167], v[216:219], v[62:65]
	v_mfma_f32_16x16x32_bf16 v[58:61], v[174:177], v[216:219], v[58:61]
	v_mfma_f32_16x16x32_bf16 v[46:49], v[164:167], v[224:227], v[46:49]
	v_mfma_f32_16x16x32_bf16 v[42:45], v[174:177], v[224:227], v[42:45]
	v_mfma_f32_16x16x32_bf16 v[30:33], v[164:167], v[232:235], v[30:33]
	v_mfma_f32_16x16x32_bf16 v[26:29], v[174:177], v[232:235], v[26:29]
	v_mfma_f32_16x16x32_bf16 v[14:17], v[164:167], v[240:243], v[14:17]
	v_mfma_f32_16x16x32_bf16 v[10:13], v[174:177], v[240:243], v[10:13]
	s_setprio 0
	s_setprio 1
	v_mfma_f32_16x16x32_bf16 v[54:57], v[178:181], v[212:215], v[54:57]
	v_mfma_f32_16x16x32_bf16 v[50:53], v[204:207], v[212:215], v[50:53]
	v_mfma_f32_16x16x32_bf16 v[38:41], v[178:181], v[220:223], v[38:41]
	v_mfma_f32_16x16x32_bf16 v[34:37], v[204:207], v[220:223], v[34:37]
	v_mfma_f32_16x16x32_bf16 v[22:25], v[178:181], v[228:231], v[22:25]
	v_mfma_f32_16x16x32_bf16 v[18:21], v[204:207], v[228:231], v[18:21]
	v_mfma_f32_16x16x32_bf16 v[6:9], v[178:181], v[236:239], v[6:9]
	v_mfma_f32_16x16x32_bf16 v[2:5], v[204:207], v[236:239], v[2:5]
	s_setprio 0
	s_setprio 1
	v_mfma_f32_16x16x32_bf16 v[54:57], v[182:185], v[216:219], v[54:57]
	v_mfma_f32_16x16x32_bf16 v[50:53], v[208:211], v[216:219], v[50:53]
	v_mfma_f32_16x16x32_bf16 v[38:41], v[182:185], v[224:227], v[38:41]
	v_mfma_f32_16x16x32_bf16 v[34:37], v[208:211], v[224:227], v[34:37]
	s_setprio 0
	v_mfma_f32_16x16x32_bf16 v[22:25], v[182:185], v[232:235], v[22:25]
	v_mfma_f32_16x16x32_bf16 v[18:21], v[208:211], v[232:235], v[18:21]
	v_mfma_f32_16x16x32_bf16 v[6:9], v[182:185], v[240:243], v[6:9]
	v_mfma_f32_16x16x32_bf16 v[2:5], v[208:211], v[240:243], v[2:5]
	s_barrier
	s_add_i32 s47, 0, 0x18000
	s_add_i32 s76, 0, 0x1c000
	v_add_u32_e32 v174, s47, v143
	v_add_u32_e32 v203, s76, v143
	ds_read_b128 v[160:163], v174
	ds_read_b128 v[164:167], v174 offset:1024
	ds_read_b128 v[170:173], v174 offset:2048
	ds_read_b128 v[174:177], v174 offset:3072
	ds_read_b128 v[178:181], v203
	ds_read_b128 v[182:185], v203 offset:1024
	ds_read_b128 v[204:207], v203 offset:2048
	ds_read_b128 v[208:211], v203 offset:3072
	s_add_u32 s36, s44, 0x60000
	s_addc_u32 s37, s45, 0
	s_mov_b32 m0, s58
	v_lshl_add_u64 v[250:251], s[36:37], 0, v[150:151]
	ds_read_b128 v[212:215], v169 offset:32768
	ds_read_b128 v[216:219], v169 offset:33792
	ds_read_b128 v[220:223], v169 offset:34816
	ds_read_b128 v[224:227], v169 offset:35840
	ds_read_b128 v[228:231], v169 offset:36864
	ds_read_b128 v[232:235], v169 offset:37888
	ds_read_b128 v[236:239], v169 offset:38912
	ds_read_b128 v[240:243], v169 offset:39936
	global_load_lds_dwordx4 v[250:251], off
	v_lshl_add_u64 v[250:251], s[36:37], 0, v[146:147]
	s_mov_b32 m0, s59
	s_nop 0
	global_load_lds_dwordx4 v[250:251], off
	s_setprio 1
	s_waitcnt vmcnt(8)
	s_waitcnt lgkmcnt(0)
	s_barrier
	v_mfma_f32_16x16x32_bf16 v[126:129], v[160:163], v[212:215], v[126:129]
	v_mfma_f32_16x16x32_bf16 v[122:125], v[170:173], v[212:215], v[122:125]
	v_mfma_f32_16x16x32_bf16 v[110:113], v[160:163], v[220:223], v[110:113]
	v_mfma_f32_16x16x32_bf16 v[106:109], v[170:173], v[220:223], v[106:109]
	v_mfma_f32_16x16x32_bf16 v[94:97], v[160:163], v[228:231], v[94:97]
	v_mfma_f32_16x16x32_bf16 v[90:93], v[170:173], v[228:231], v[90:93]
	v_mfma_f32_16x16x32_bf16 v[78:81], v[160:163], v[236:239], v[78:81]
	v_mfma_f32_16x16x32_bf16 v[74:77], v[170:173], v[236:239], v[74:77]
	s_setprio 0
	s_setprio 1
	v_mfma_f32_16x16x32_bf16 v[126:129], v[164:167], v[216:219], v[126:129]
	v_mfma_f32_16x16x32_bf16 v[122:125], v[174:177], v[216:219], v[122:125]
	v_mfma_f32_16x16x32_bf16 v[110:113], v[164:167], v[224:227], v[110:113]
	v_mfma_f32_16x16x32_bf16 v[106:109], v[174:177], v[224:227], v[106:109]
	v_mfma_f32_16x16x32_bf16 v[94:97], v[164:167], v[232:235], v[94:97]
	v_mfma_f32_16x16x32_bf16 v[90:93], v[174:177], v[232:235], v[90:93]
	v_mfma_f32_16x16x32_bf16 v[78:81], v[164:167], v[240:243], v[78:81]
	v_mfma_f32_16x16x32_bf16 v[74:77], v[174:177], v[240:243], v[74:77]
	s_setprio 0
	s_setprio 1
	v_mfma_f32_16x16x32_bf16 v[118:121], v[178:181], v[212:215], v[118:121]
	v_mfma_f32_16x16x32_bf16 v[114:117], v[204:207], v[212:215], v[114:117]
	v_mfma_f32_16x16x32_bf16 v[102:105], v[178:181], v[220:223], v[102:105]
	v_mfma_f32_16x16x32_bf16 v[98:101], v[204:207], v[220:223], v[98:101]
	v_mfma_f32_16x16x32_bf16 v[86:89], v[178:181], v[228:231], v[86:89]
	v_mfma_f32_16x16x32_bf16 v[82:85], v[204:207], v[228:231], v[82:85]
	v_mfma_f32_16x16x32_bf16 v[70:73], v[178:181], v[236:239], v[70:73]
	v_mfma_f32_16x16x32_bf16 v[66:69], v[204:207], v[236:239], v[66:69]
	s_setprio 0
	s_setprio 1
	v_mfma_f32_16x16x32_bf16 v[118:121], v[182:185], v[216:219], v[118:121]
	v_mfma_f32_16x16x32_bf16 v[114:117], v[208:211], v[216:219], v[114:117]
	v_mfma_f32_16x16x32_bf16 v[102:105], v[182:185], v[224:227], v[102:105]
	v_mfma_f32_16x16x32_bf16 v[98:101], v[208:211], v[224:227], v[98:101]
	s_setprio 0
	v_mfma_f32_16x16x32_bf16 v[86:89], v[182:185], v[232:235], v[86:89]
	v_mfma_f32_16x16x32_bf16 v[82:85], v[208:211], v[232:235], v[82:85]
	v_mfma_f32_16x16x32_bf16 v[70:73], v[182:185], v[240:243], v[70:73]
	v_mfma_f32_16x16x32_bf16 v[66:69], v[208:211], v[240:243], v[66:69]
	s_barrier
; #define PG8_STAGE(bufoff, gbase, voff) do { _Pragma("unroll") for (int _i = 0; _i < 2; ++_i) \
;         __builtin_amdgcn_global_load_lds((const unsigned*)((const char*)(gbase) + (voff)[_i]), (PG8_LAS unsigned*)(lds + (bufoff) + ldsw + _i * 8192), 16, 0, 0); } while (0)
; #define PG8_LDA(dst, b, h) do { _Pragma("unroll") for (int m = 0; m < 4; ++m) _Pragma("unroll") for (int k = 0; k < 2; ++k) dst[m][k] = *(const PG8_LAS bf16x8*)(lds + PG8_SA(b, h) + aoff + m * 2048 + k * 1024); } while (0)
; #define PG8_MMA(ai, bj, At, Bt) do { __builtin_amdgcn_s_setprio(1); _Pragma("unroll") for (int m = 0; m < 4; ++m) _Pragma("unroll") for (int n = 0; n < 2; ++n) _Pragma("unroll") for (int k = 0; k < 2; ++k) \
;         acc[ai][bj][m][n] = __builtin_amdgcn_mfma_f32_16x16x32_bf16(Bt[n][k], At[m][k], acc[ai][bj][m][n], 0, 0, 0); __builtin_amdgcn_s_setprio(0); } while (0)
; #define PG8_WAIT_V(n) asm volatile("s_waitcnt vmcnt(" #n ")" ::: "memory")
; #define PG8_WAIT_L(n) asm volatile("s_waitcnt lgkmcnt(" #n ")" ::: "memory")
; #define PG8_BAR __builtin_amdgcn_s_barrier()
; #define PG8_SCHED __builtin_amdgcn_sched_barrier(0)
; template <class Epi, class Sched, bool ALIGN_EPI = false, bool SP2 = false>
; __device__ __forceinline__ void gemm_phase(PG8_LAS unsigned char* lds, const Gemm g, const Sched& S, const Epi& E) {
;     ...
;             PG8_LDA(At, 1, 1); PG8_STAGE(PG8_SB(1, 0), b3, voffB); PG8_STAGE(PG8_SB(1, 1), b3 + hstep, voffB); PG8_STAGE(PG8_SA(1, 0), a3, voffA);
;             PG8_WAIT_V(8); PG8_WAIT_L(0); PG8_BAR; PG8_MMA(1, 0, At, B0); PG8_MMA(1, 1, At, B1); PG8_BAR; PG8_SCHED;
;     ...
;         if constexpr (ALIGN_EPI) { if (wr == 0) PG8_BAR; }
	s_add_i32 s36, s47, s4
	v_lshl_add_u64 v[186:187], v[186:187], 0, s[68:69]
	s_mov_b32 m0, s36
	ds_read_b128 v[212:215], v169 offset:49152
	ds_read_b128 v[216:219], v169 offset:50176
	ds_read_b128 v[220:223], v169 offset:51200
	ds_read_b128 v[224:227], v169 offset:52224
	ds_read_b128 v[228:231], v169 offset:53248
	ds_read_b128 v[232:235], v169 offset:54272
	ds_read_b128 v[236:239], v169 offset:55296
	ds_read_b128 v[240:243], v169 offset:56320
	global_load_lds_dwordx4 v[186:187], off
	s_add_i32 m0, s36, 0x2000
	s_add_u32 s18, s18, 0x60080
	v_lshl_add_u64 v[186:187], v[244:245], 0, s[68:69]
	s_addc_u32 s19, s19, 0
	s_add_i32 s36, s76, s4
	global_load_lds_dwordx4 v[186:187], off
	v_lshl_add_u64 v[186:187], s[18:19], 0, v[148:149]
	s_mov_b32 m0, s36
	s_nop 0
	global_load_lds_dwordx4 v[186:187], off
	v_lshl_add_u64 v[186:187], s[18:19], 0, v[144:145]
	s_add_i32 m0, s36, 0x2000
	s_nop 0
	global_load_lds_dwordx4 v[186:187], off
	v_lshl_add_u64 v[186:187], v[246:247], 0, s[68:69]
	s_mov_b32 m0, s62
	s_nop 0
	global_load_lds_dwordx4 v[186:187], off
	v_lshl_add_u64 v[186:187], v[248:249], 0, s[68:69]
	s_mov_b32 m0, s63
	s_nop 0
	global_load_lds_dwordx4 v[186:187], off
	s_nop 0
	s_setprio 1
	s_waitcnt vmcnt(8)
	s_waitcnt lgkmcnt(0)
	s_barrier
	v_mfma_f32_16x16x32_bf16 v[62:65], v[160:163], v[212:215], v[62:65]
	v_mfma_f32_16x16x32_bf16 v[58:61], v[170:173], v[212:215], v[58:61]
	v_mfma_f32_16x16x32_bf16 v[46:49], v[160:163], v[220:223], v[46:49]
	v_mfma_f32_16x16x32_bf16 v[42:45], v[170:173], v[220:223], v[42:45]
	v_mfma_f32_16x16x32_bf16 v[30:33], v[160:163], v[228:231], v[30:33]
	v_mfma_f32_16x16x32_bf16 v[26:29], v[170:173], v[228:231], v[26:29]
	v_mfma_f32_16x16x32_bf16 v[14:17], v[160:163], v[236:239], v[14:17]
	v_mfma_f32_16x16x32_bf16 v[10:13], v[170:173], v[236:239], v[10:13]
	s_setprio 0
	s_setprio 1
	v_mfma_f32_16x16x32_bf16 v[62:65], v[164:167], v[216:219], v[62:65]
	v_mfma_f32_16x16x32_bf16 v[58:61], v[174:177], v[216:219], v[58:61]
	v_mfma_f32_16x16x32_bf16 v[46:49], v[164:167], v[224:227], v[46:49]
	v_mfma_f32_16x16x32_bf16 v[42:45], v[174:177], v[224:227], v[42:45]
	v_mfma_f32_16x16x32_bf16 v[30:33], v[164:167], v[232:235], v[30:33]
	v_mfma_f32_16x16x32_bf16 v[26:29], v[174:177], v[232:235], v[26:29]
	v_mfma_f32_16x16x32_bf16 v[14:17], v[164:167], v[240:243], v[14:17]
	v_mfma_f32_16x16x32_bf16 v[10:13], v[174:177], v[240:243], v[10:13]
	s_setprio 0
	s_setprio 1
	v_mfma_f32_16x16x32_bf16 v[54:57], v[178:181], v[212:215], v[54:57]
	v_mfma_f32_16x16x32_bf16 v[50:53], v[204:207], v[212:215], v[50:53]
	v_mfma_f32_16x16x32_bf16 v[38:41], v[178:181], v[220:223], v[38:41]
	v_mfma_f32_16x16x32_bf16 v[34:37], v[204:207], v[220:223], v[34:37]
	v_mfma_f32_16x16x32_bf16 v[22:25], v[178:181], v[228:231], v[22:25]
	v_mfma_f32_16x16x32_bf16 v[18:21], v[204:207], v[228:231], v[18:21]
	v_mfma_f32_16x16x32_bf16 v[6:9], v[178:181], v[236:239], v[6:9]
	v_mfma_f32_16x16x32_bf16 v[2:5], v[204:207], v[236:239], v[2:5]
	s_setprio 0
	s_setprio 1
	v_mfma_f32_16x16x32_bf16 v[54:57], v[182:185], v[216:219], v[54:57]
	v_mfma_f32_16x16x32_bf16 v[50:53], v[208:211], v[216:219], v[50:53]
	v_mfma_f32_16x16x32_bf16 v[38:41], v[182:185], v[224:227], v[38:41]
	v_mfma_f32_16x16x32_bf16 v[34:37], v[208:211], v[224:227], v[34:37]
	s_setprio 0
	v_mfma_f32_16x16x32_bf16 v[22:25], v[182:185], v[232:235], v[22:25]
	v_mfma_f32_16x16x32_bf16 v[18:21], v[208:211], v[232:235], v[18:21]
	v_mfma_f32_16x16x32_bf16 v[6:9], v[182:185], v[240:243], v[6:9]
	v_mfma_f32_16x16x32_bf16 v[2:5], v[208:211], v[240:243], v[2:5]
	s_barrier
	s_add_i32 s46, s46, 2
	s_add_u32 s60, s60, 0x100
	s_addc_u32 s73, s73, 0
	s_cmp_gt_u32 s46, 21
	s_mov_b64 s[36:37], s[42:43]
	s_cbranch_scc0 .LBB0_160
	s_and_b64 vcc, exec, s[10:11]
	s_cbranch_vccz .LBB0_163
	s_barrier

; #define PG8_STAGE(bufoff, gbase, voff) do { _Pragma("unroll") for (int _i = 0; _i < 2; ++_i) \
;         __builtin_amdgcn_global_load_lds((const unsigned*)((const char*)(gbase) + (voff)[_i]), (PG8_LAS unsigned*)(lds + (bufoff) + ldsw + _i * 8192), 16, 0, 0); } while (0)
; #define PG8_LDA(dst, b, h) do { _Pragma("unroll") for (int m = 0; m < 4; ++m) _Pragma("unroll") for (int k = 0; k < 2; ++k) dst[m][k] = *(const PG8_LAS bf16x8*)(lds + PG8_SA(b, h) + aoff + m * 2048 + k * 1024); } while (0)
; #define PG8_LDB(dst, b, h) do { _Pragma("unroll") for (int n = 0; n < 2; ++n) _Pragma("unroll") for (int k = 0; k < 2; ++k) dst[n][k] = *(const PG8_LAS bf16x8*)(lds + PG8_SB(b, h) + boff + n * 2048 + k * 1024); } while (0)
; #define PG8_MMA(ai, bj, At, Bt) do { __builtin_amdgcn_s_setprio(1); _Pragma("unroll") for (int m = 0; m < 4; ++m) _Pragma("unroll") for (int n = 0; n < 2; ++n) _Pragma("unroll") for (int k = 0; k < 2; ++k) \
;         acc[ai][bj][m][n] = __builtin_amdgcn_mfma_f32_16x16x32_bf16(Bt[n][k], At[m][k], acc[ai][bj][m][n], 0, 0, 0); __builtin_amdgcn_s_setprio(0); } while (0)
; #define PG8_WAIT_V(n) asm volatile("s_waitcnt vmcnt(" #n ")" ::: "memory")
; #define PG8_WAIT_L(n) asm volatile("s_waitcnt lgkmcnt(" #n ")" ::: "memory")
; template <class Epi, class Sched, bool ALIGN_EPI = false, bool SP2 = false>
; __device__ __forceinline__ void gemm_phase(PG8_LAS unsigned char* lds, const Gemm g, const Sched& S, const Epi& E) {
;     ...
;             const bool last = (t == nt - 2);
;             const char* a1 = cA + (size_t)(t + 1) * kstep;
;             const char* a2 = last ? nA : cA + (size_t)(t + 2) * kstep; const char* b2 = last ? nB : cB + (size_t)(t + 2) * kstep;
;             const char* a3 = a2 + kstep; const char* b3 = b2 + kstep;
;             if (last && has_next) S.a_ready(nxt);
;             if constexpr (SP2) {
;             PG8_LDB(B0, 0, 0); PG8_LDB(B1, 0, 1); PG8_SCHED; PG8_LDA(At, 0, 0); PG8_STAGE(PG8_SA(1, 1), a1 + hstep, voffA);
;             PG8_WAIT_V(8); PG8_WAIT_L(0); PG8_BAR; PG8_MMA(0, 0, At, B0); PG8_MMA(0, 1, At, B1); PG8_BAR; PG8_SCHED;
;             PG8_LDA(At, 0, 1); PG8_STAGE(PG8_SB(0, 0), b2, voffB); PG8_STAGE(PG8_SB(0, 1), b2 + hstep, voffB); PG8_STAGE(PG8_SA(0, 0), a2, voffA);
;             PG8_WAIT_V(8); PG8_WAIT_L(0); PG8_BAR; PG8_MMA(1, 0, At, B0); PG8_MMA(1, 1, At, B1); PG8_BAR; PG8_SCHED;
.LBB0_281:
	s_add_u32 s18, s36, 0xfff80080
	s_addc_u32 s19, s37, -1
	s_add_i32 s73, 0, 0x10000
	s_cmp_eq_u32 s67, 28
	s_cselect_b32 s43, s9, s19
	s_cselect_b32 s42, s59, s18
	v_add_u32_e32 v163, s73, v160
	s_cselect_b32 s19, s7, s63
	s_cselect_b32 s18, s60, s62
	s_add_i32 s76, 0, 0x14000
	ds_read_b128 v[156:159], v163
	ds_read_b128 v[164:167], v163 offset:1024
	ds_read_b128 v[168:171], v163 offset:2048
	ds_read_b128 v[172:175], v163 offset:3072
	v_add_u32_e32 v163, s76, v160
	ds_read_b128 v[176:179], v163
	ds_read_b128 v[180:183], v163 offset:1024
	ds_read_b128 v[184:187], v163 offset:2048
	ds_read_b128 v[204:207], v163 offset:3072
	v_lshl_add_u64 v[240:241], s[36:37], 0, v[152:153]
	s_add_i32 m0, s30, 0xc000
	ds_read_b128 v[208:211], v162
	ds_read_b128 v[212:215], v162 offset:1024
	ds_read_b128 v[216:219], v162 offset:2048
	ds_read_b128 v[220:223], v162 offset:3072
	ds_read_b128 v[224:227], v162 offset:4096
	ds_read_b128 v[228:231], v162 offset:5120
	ds_read_b128 v[232:235], v162 offset:6144
	ds_read_b128 v[236:239], v162 offset:7168
	global_load_lds_dwordx4 v[240:241], off
	v_lshl_add_u64 v[240:241], s[36:37], 0, v[154:155]
	s_add_i32 m0, s30, 0xe000
	s_nop 0
	global_load_lds_dwordx4 v[240:241], off
	s_nop 0
	s_nop 0
	s_setprio 1
	s_waitcnt vmcnt(8)
	s_waitcnt lgkmcnt(0)
	s_barrier
	v_mfma_f32_16x16x32_bf16 v[126:129], v[156:159], v[208:211], v[126:129]
	v_mfma_f32_16x16x32_bf16 v[122:125], v[168:171], v[208:211], v[122:125]
	v_mfma_f32_16x16x32_bf16 v[110:113], v[156:159], v[216:219], v[110:113]
	v_mfma_f32_16x16x32_bf16 v[106:109], v[168:171], v[216:219], v[106:109]
	v_mfma_f32_16x16x32_bf16 v[94:97], v[156:159], v[224:227], v[94:97]
	v_mfma_f32_16x16x32_bf16 v[90:93], v[168:171], v[224:227], v[90:93]
	v_mfma_f32_16x16x32_bf16 v[78:81], v[156:159], v[232:235], v[78:81]
	v_mfma_f32_16x16x32_bf16 v[74:77], v[168:171], v[232:235], v[74:77]
	s_setprio 0
	s_setprio 1
	v_mfma_f32_16x16x32_bf16 v[126:129], v[164:167], v[212:215], v[126:129]
	v_mfma_f32_16x16x32_bf16 v[122:125], v[172:175], v[212:215], v[122:125]
	v_mfma_f32_16x16x32_bf16 v[110:113], v[164:167], v[220:223], v[110:113]
	v_mfma_f32_16x16x32_bf16 v[106:109], v[172:175], v[220:223], v[106:109]
	v_mfma_f32_16x16x32_bf16 v[94:97], v[164:167], v[228:231], v[94:97]
	v_mfma_f32_16x16x32_bf16 v[90:93], v[172:175], v[228:231], v[90:93]
	v_mfma_f32_16x16x32_bf16 v[78:81], v[164:167], v[236:239], v[78:81]
	v_mfma_f32_16x16x32_bf16 v[74:77], v[172:175], v[236:239], v[74:77]
	s_setprio 0
	s_setprio 1
	v_mfma_f32_16x16x32_bf16 v[118:121], v[176:179], v[208:211], v[118:121]
	v_mfma_f32_16x16x32_bf16 v[114:117], v[184:187], v[208:211], v[114:117]
	v_mfma_f32_16x16x32_bf16 v[102:105], v[176:179], v[216:219], v[102:105]
	v_mfma_f32_16x16x32_bf16 v[98:101], v[184:187], v[216:219], v[98:101]
	v_mfma_f32_16x16x32_bf16 v[86:89], v[176:179], v[224:227], v[86:89]
	v_mfma_f32_16x16x32_bf16 v[82:85], v[184:187], v[224:227], v[82:85]
	v_mfma_f32_16x16x32_bf16 v[70:73], v[176:179], v[232:235], v[70:73]
	v_mfma_f32_16x16x32_bf16 v[66:69], v[184:187], v[232:235], v[66:69]
	s_setprio 0
	s_setprio 1
	v_mfma_f32_16x16x32_bf16 v[118:121], v[180:183], v[212:215], v[118:121]
	v_mfma_f32_16x16x32_bf16 v[114:117], v[204:207], v[212:215], v[114:117]
	v_mfma_f32_16x16x32_bf16 v[102:105], v[180:183], v[220:223], v[102:105]
	v_mfma_f32_16x16x32_bf16 v[98:101], v[204:207], v[220:223], v[98:101]
	s_setprio 0
	v_mfma_f32_16x16x32_bf16 v[86:89], v[180:183], v[228:231], v[86:89]
	v_mfma_f32_16x16x32_bf16 v[82:85], v[204:207], v[228:231], v[82:85]
	v_mfma_f32_16x16x32_bf16 v[70:73], v[180:183], v[236:239], v[70:73]
	v_mfma_f32_16x16x32_bf16 v[66:69], v[204:207], v[236:239], v[66:69]
	s_barrier
	s_add_i32 s73, s73, s28
	v_lshl_add_u64 v[240:241], s[18:19], 0, v[146:147]
	s_mov_b32 m0, s73
	ds_read_b128 v[208:211], v162 offset:16384
	ds_read_b128 v[212:215], v162 offset:17408
	ds_read_b128 v[216:219], v162 offset:18432
	ds_read_b128 v[220:223], v162 offset:19456
	ds_read_b128 v[224:227], v162 offset:20480
	ds_read_b128 v[228:231], v162 offset:21504
	ds_read_b128 v[232:235], v162 offset:22528
	ds_read_b128 v[236:239], v162 offset:23552
	global_load_lds_dwordx4 v[240:241], off
	s_add_i32 m0, s73, 0x2000
	s_add_u32 s78, s18, 0x80000
	v_lshl_add_u64 v[242:243], s[18:19], 0, v[142:143]
	s_addc_u32 s79, s19, 0
	s_add_i32 s73, s76, s28
	global_load_lds_dwordx4 v[242:243], off
	v_lshl_add_u64 v[244:245], s[78:79], 0, v[146:147]
	s_mov_b32 m0, s73
	v_lshl_add_u64 v[246:247], s[42:43], 0, v[144:145]
	global_load_lds_dwordx4 v[244:245], off
	v_lshl_add_u64 v[244:245], s[78:79], 0, v[142:143]
	s_add_i32 m0, s73, 0x2000
	s_nop 0
	global_load_lds_dwordx4 v[244:245], off
	v_lshl_add_u64 v[244:245], s[42:43], 0, v[148:149]
	s_mov_b32 m0, s30
	s_nop 0
	global_load_lds_dwordx4 v[244:245], off
	s_mov_b32 m0, s34
	s_nop 0
	global_load_lds_dwordx4 v[246:247], off
	s_setprio 1
	s_waitcnt vmcnt(8)
	s_waitcnt lgkmcnt(0)
	s_barrier
; #define PG8_STAGE(bufoff, gbase, voff) do { _Pragma("unroll") for (int _i = 0; _i < 2; ++_i) \
;         __builtin_amdgcn_global_load_lds((const unsigned*)((const char*)(gbase) + (voff)[_i]), (PG8_LAS unsigned*)(lds + (bufoff) + ldsw + _i * 8192), 16, 0, 0); } while (0)
; #define PG8_LDA(dst, b, h) do { _Pragma("unroll") for (int m = 0; m < 4; ++m) _Pragma("unroll") for (int k = 0; k < 2; ++k) dst[m][k] = *(const PG8_LAS bf16x8*)(lds + PG8_SA(b, h) + aoff + m * 2048 + k * 1024); } while (0)
; #define PG8_LDB(dst, b, h) do { _Pragma("unroll") for (int n = 0; n < 2; ++n) _Pragma("unroll") for (int k = 0; k < 2; ++k) dst[n][k] = *(const PG8_LAS bf16x8*)(lds + PG8_SB(b, h) + boff + n * 2048 + k * 1024); } while (0)
; #define PG8_MMA(ai, bj, At, Bt) do { __builtin_amdgcn_s_setprio(1); _Pragma("unroll") for (int m = 0; m < 4; ++m) _Pragma("unroll") for (int n = 0; n < 2; ++n) _Pragma("unroll") for (int k = 0; k < 2; ++k) \
;         acc[ai][bj][m][n] = __builtin_amdgcn_mfma_f32_16x16x32_bf16(Bt[n][k], At[m][k], acc[ai][bj][m][n], 0, 0, 0); __builtin_amdgcn_s_setprio(0); } while (0)
; #define PG8_WAIT_V(n) asm volatile("s_waitcnt vmcnt(" #n ")" ::: "memory")
; #define PG8_WAIT_L(n) asm volatile("s_waitcnt lgkmcnt(" #n ")" ::: "memory")
; #define PG8_BAR __builtin_amdgcn_s_barrier()
; #define PG8_SCHED __builtin_amdgcn_sched_barrier(0)
; template <class Epi, class Sched, bool ALIGN_EPI = false, bool SP2 = false>
; __device__ __forceinline__ void gemm_phase(PG8_LAS unsigned char* lds, const Gemm g, const Sched& S, const Epi& E) {
;     ...
;             PG8_WAIT_V(8); PG8_WAIT_L(0); PG8_BAR; PG8_MMA(1, 0, At, B0); PG8_MMA(1, 1, At, B1); PG8_BAR; PG8_SCHED;
;             PG8_LDB(B0, 1, 0); PG8_LDB(B1, 1, 1); PG8_SCHED; PG8_LDA(At, 1, 0); PG8_STAGE(PG8_SA(0, 1), a2 + hstep, voffA);
;             PG8_WAIT_V(8); PG8_WAIT_L(0); PG8_BAR; PG8_MMA(0, 0, At, B0); PG8_MMA(0, 1, At, B1); PG8_BAR; PG8_SCHED;
	v_mfma_f32_16x16x32_bf16 v[62:65], v[156:159], v[208:211], v[62:65]
	v_mfma_f32_16x16x32_bf16 v[58:61], v[168:171], v[208:211], v[58:61]
	v_mfma_f32_16x16x32_bf16 v[46:49], v[156:159], v[216:219], v[46:49]
	v_mfma_f32_16x16x32_bf16 v[42:45], v[168:171], v[216:219], v[42:45]
	v_mfma_f32_16x16x32_bf16 v[30:33], v[156:159], v[224:227], v[30:33]
	v_mfma_f32_16x16x32_bf16 v[26:29], v[168:171], v[224:227], v[26:29]
	v_mfma_f32_16x16x32_bf16 v[14:17], v[156:159], v[232:235], v[14:17]
	v_mfma_f32_16x16x32_bf16 v[10:13], v[168:171], v[232:235], v[10:13]
	s_setprio 0
	s_setprio 1
	v_mfma_f32_16x16x32_bf16 v[62:65], v[164:167], v[212:215], v[62:65]
	v_mfma_f32_16x16x32_bf16 v[58:61], v[172:175], v[212:215], v[58:61]
	v_mfma_f32_16x16x32_bf16 v[46:49], v[164:167], v[220:223], v[46:49]
	v_mfma_f32_16x16x32_bf16 v[42:45], v[172:175], v[220:223], v[42:45]
	v_mfma_f32_16x16x32_bf16 v[30:33], v[164:167], v[228:231], v[30:33]
	v_mfma_f32_16x16x32_bf16 v[26:29], v[172:175], v[228:231], v[26:29]
	v_mfma_f32_16x16x32_bf16 v[14:17], v[164:167], v[236:239], v[14:17]
	v_mfma_f32_16x16x32_bf16 v[10:13], v[172:175], v[236:239], v[10:13]
	s_setprio 0
	s_setprio 1
	v_mfma_f32_16x16x32_bf16 v[54:57], v[176:179], v[208:211], v[54:57]
	v_mfma_f32_16x16x32_bf16 v[50:53], v[184:187], v[208:211], v[50:53]
	v_mfma_f32_16x16x32_bf16 v[38:41], v[176:179], v[216:219], v[38:41]
	v_mfma_f32_16x16x32_bf16 v[34:37], v[184:187], v[216:219], v[34:37]
	v_mfma_f32_16x16x32_bf16 v[22:25], v[176:179], v[224:227], v[22:25]
	v_mfma_f32_16x16x32_bf16 v[18:21], v[184:187], v[224:227], v[18:21]
	v_mfma_f32_16x16x32_bf16 v[6:9], v[176:179], v[232:235], v[6:9]
	v_mfma_f32_16x16x32_bf16 v[2:5], v[184:187], v[232:235], v[2:5]
	s_setprio 0
	s_setprio 1
	v_mfma_f32_16x16x32_bf16 v[54:57], v[180:183], v[212:215], v[54:57]
	v_mfma_f32_16x16x32_bf16 v[50:53], v[204:207], v[212:215], v[50:53]
	v_mfma_f32_16x16x32_bf16 v[38:41], v[180:183], v[220:223], v[38:41]
	v_mfma_f32_16x16x32_bf16 v[34:37], v[204:207], v[220:223], v[34:37]
	s_setprio 0
	v_mfma_f32_16x16x32_bf16 v[22:25], v[180:183], v[228:231], v[22:25]
	v_mfma_f32_16x16x32_bf16 v[18:21], v[204:207], v[228:231], v[18:21]
	v_mfma_f32_16x16x32_bf16 v[6:9], v[180:183], v[236:239], v[6:9]
	v_mfma_f32_16x16x32_bf16 v[2:5], v[204:207], v[236:239], v[2:5]
	s_barrier
	s_add_i32 s73, 0, 0x18000
	v_add_u32_e32 v163, s73, v160
	s_add_i32 s76, 0, 0x1c000
	ds_read_b128 v[156:159], v163
	ds_read_b128 v[164:167], v163 offset:1024
	ds_read_b128 v[168:171], v163 offset:2048
	ds_read_b128 v[172:175], v163 offset:3072
	v_add_u32_e32 v163, s76, v160
	ds_read_b128 v[176:179], v163
	ds_read_b128 v[180:183], v163 offset:1024
	ds_read_b128 v[184:187], v163 offset:2048
	ds_read_b128 v[204:207], v163 offset:3072
	s_add_u32 s42, s42, 0x80000
	s_addc_u32 s43, s43, 0
	s_mov_b32 m0, s44
	v_lshl_add_u64 v[248:249], s[42:43], 0, v[148:149]
	ds_read_b128 v[208:211], v162 offset:32768
	ds_read_b128 v[212:215], v162 offset:33792
	ds_read_b128 v[216:219], v162 offset:34816
	ds_read_b128 v[220:223], v162 offset:35840
	ds_read_b128 v[224:227], v162 offset:36864
	ds_read_b128 v[228:231], v162 offset:37888
	ds_read_b128 v[232:235], v162 offset:38912
	ds_read_b128 v[236:239], v162 offset:39936
	global_load_lds_dwordx4 v[248:249], off
	v_lshl_add_u64 v[248:249], s[42:43], 0, v[144:145]
	s_mov_b32 m0, s45
	s_nop 0
	global_load_lds_dwordx4 v[248:249], off
	s_setprio 1
	s_waitcnt vmcnt(8)
	s_waitcnt lgkmcnt(0)
	s_barrier
	v_mfma_f32_16x16x32_bf16 v[126:129], v[156:159], v[208:211], v[126:129]
	v_mfma_f32_16x16x32_bf16 v[122:125], v[168:171], v[208:211], v[122:125]
	v_mfma_f32_16x16x32_bf16 v[110:113], v[156:159], v[216:219], v[110:113]
	v_mfma_f32_16x16x32_bf16 v[106:109], v[168:171], v[216:219], v[106:109]
	v_mfma_f32_16x16x32_bf16 v[94:97], v[156:159], v[224:227], v[94:97]
	v_mfma_f32_16x16x32_bf16 v[90:93], v[168:171], v[224:227], v[90:93]
	v_mfma_f32_16x16x32_bf16 v[78:81], v[156:159], v[232:235], v[78:81]
	v_mfma_f32_16x16x32_bf16 v[74:77], v[168:171], v[232:235], v[74:77]
	s_setprio 0
	s_setprio 1
	v_mfma_f32_16x16x32_bf16 v[126:129], v[164:167], v[212:215], v[126:129]
	v_mfma_f32_16x16x32_bf16 v[122:125], v[172:175], v[212:215], v[122:125]
	v_mfma_f32_16x16x32_bf16 v[110:113], v[164:167], v[220:223], v[110:113]
	v_mfma_f32_16x16x32_bf16 v[106:109], v[172:175], v[220:223], v[106:109]
	v_mfma_f32_16x16x32_bf16 v[94:97], v[164:167], v[228:231], v[94:97]
	v_mfma_f32_16x16x32_bf16 v[90:93], v[172:175], v[228:231], v[90:93]
	v_mfma_f32_16x16x32_bf16 v[78:81], v[164:167], v[236:239], v[78:81]
	v_mfma_f32_16x16x32_bf16 v[74:77], v[172:175], v[236:239], v[74:77]
	s_setprio 0
	s_setprio 1
	v_mfma_f32_16x16x32_bf16 v[118:121], v[176:179], v[208:211], v[118:121]
	v_mfma_f32_16x16x32_bf16 v[114:117], v[184:187], v[208:211], v[114:117]
	v_mfma_f32_16x16x32_bf16 v[102:105], v[176:179], v[216:219], v[102:105]
	v_mfma_f32_16x16x32_bf16 v[98:101], v[184:187], v[216:219], v[98:101]
	v_mfma_f32_16x16x32_bf16 v[86:89], v[176:179], v[224:227], v[86:89]
	v_mfma_f32_16x16x32_bf16 v[82:85], v[184:187], v[224:227], v[82:85]
	v_mfma_f32_16x16x32_bf16 v[70:73], v[176:179], v[232:235], v[70:73]
	v_mfma_f32_16x16x32_bf16 v[66:69], v[184:187], v[232:235], v[66:69]
	s_setprio 0
	s_setprio 1
	v_mfma_f32_16x16x32_bf16 v[118:121], v[180:183], v[212:215], v[118:121]
	v_mfma_f32_16x16x32_bf16 v[114:117], v[204:207], v[212:215], v[114:117]
	v_mfma_f32_16x16x32_bf16 v[102:105], v[180:183], v[220:223], v[102:105]
	v_mfma_f32_16x16x32_bf16 v[98:101], v[204:207], v[220:223], v[98:101]
	s_setprio 0
	v_mfma_f32_16x16x32_bf16 v[86:89], v[180:183], v[228:231], v[86:89]
	v_mfma_f32_16x16x32_bf16 v[82:85], v[204:207], v[228:231], v[82:85]
	v_mfma_f32_16x16x32_bf16 v[70:73], v[180:183], v[236:239], v[70:73]
	v_mfma_f32_16x16x32_bf16 v[66:69], v[204:207], v[236:239], v[66:69]
	s_barrier
; #define PG8_STAGE(bufoff, gbase, voff) do { _Pragma("unroll") for (int _i = 0; _i < 2; ++_i) \
;         __builtin_amdgcn_global_load_lds((const unsigned*)((const char*)(gbase) + (voff)[_i]), (PG8_LAS unsigned*)(lds + (bufoff) + ldsw + _i * 8192), 16, 0, 0); } while (0)
; #define PG8_LDA(dst, b, h) do { _Pragma("unroll") for (int m = 0; m < 4; ++m) _Pragma("unroll") for (int k = 0; k < 2; ++k) dst[m][k] = *(const PG8_LAS bf16x8*)(lds + PG8_SA(b, h) + aoff + m * 2048 + k * 1024); } while (0)
; #define PG8_MMA(ai, bj, At, Bt) do { __builtin_amdgcn_s_setprio(1); _Pragma("unroll") for (int m = 0; m < 4; ++m) _Pragma("unroll") for (int n = 0; n < 2; ++n) _Pragma("unroll") for (int k = 0; k < 2; ++k) \
;         acc[ai][bj][m][n] = __builtin_amdgcn_mfma_f32_16x16x32_bf16(Bt[n][k], At[m][k], acc[ai][bj][m][n], 0, 0, 0); __builtin_amdgcn_s_setprio(0); } while (0)
; #define PG8_WAIT_V(n) asm volatile("s_waitcnt vmcnt(" #n ")" ::: "memory")
; #define PG8_WAIT_L(n) asm volatile("s_waitcnt lgkmcnt(" #n ")" ::: "memory")
; #define PG8_BAR __builtin_amdgcn_s_barrier()
; #define PG8_SCHED __builtin_amdgcn_sched_barrier(0)
;     __device__ __forceinline__ void operator()(const f32x4 (&acc)[2][2][4][2], const Unit& u, int wr, int wc, int fr, int fq) const {
;     ...
;         if (u.pn >= 30) {
;             const int tidn = (wr * 4 + wc) * 64 + fq * 16 + fr;
; template <class Epi, class Sched, bool ALIGN_EPI = false, bool SP2 = false>
; __device__ __forceinline__ void gemm_phase(PG8_LAS unsigned char* lds, const Gemm g, const Sched& S, const Epi& E) {
;     ...
;             PG8_LDA(At, 1, 1); PG8_STAGE(PG8_SB(1, 0), b3, voffB); PG8_STAGE(PG8_SB(1, 1), b3 + hstep, voffB); PG8_STAGE(PG8_SA(1, 0), a3, voffA);
;             PG8_WAIT_V(8); PG8_WAIT_L(0); PG8_BAR; PG8_MMA(1, 0, At, B0); PG8_MMA(1, 1, At, B1); PG8_BAR; PG8_SCHED;
	s_add_i32 s42, s73, s28
	v_lshl_add_u64 v[240:241], v[240:241], 0, s[68:69]
	s_mov_b32 m0, s42
	ds_read_b128 v[208:211], v162 offset:49152
	ds_read_b128 v[212:215], v162 offset:50176
	ds_read_b128 v[216:219], v162 offset:51200
	ds_read_b128 v[220:223], v162 offset:52224
	ds_read_b128 v[224:227], v162 offset:53248
	ds_read_b128 v[228:231], v162 offset:54272
	ds_read_b128 v[232:235], v162 offset:55296
	ds_read_b128 v[236:239], v162 offset:56320
	global_load_lds_dwordx4 v[240:241], off
	s_add_i32 m0, s42, 0x2000
	s_add_u32 s18, s18, 0x80080
	v_lshl_add_u64 v[240:241], v[242:243], 0, s[68:69]
	s_addc_u32 s19, s19, 0
	s_add_i32 s42, s76, s28
	global_load_lds_dwordx4 v[240:241], off
	v_lshl_add_u64 v[240:241], s[18:19], 0, v[146:147]
	s_mov_b32 m0, s42
	s_nop 0
	global_load_lds_dwordx4 v[240:241], off
	v_lshl_add_u64 v[240:241], s[18:19], 0, v[142:143]
	s_add_i32 m0, s42, 0x2000
	s_nop 0
	global_load_lds_dwordx4 v[240:241], off
	v_lshl_add_u64 v[240:241], v[244:245], 0, s[68:69]
	s_mov_b32 m0, s46
	s_nop 0
	global_load_lds_dwordx4 v[240:241], off
	v_lshl_add_u64 v[240:241], v[246:247], 0, s[68:69]
	s_mov_b32 m0, s47
	s_nop 0
	global_load_lds_dwordx4 v[240:241], off
	s_nop 0
	s_setprio 1
	s_waitcnt vmcnt(8)
	s_waitcnt lgkmcnt(0)
	s_barrier
	v_mfma_f32_16x16x32_bf16 v[62:65], v[156:159], v[208:211], v[62:65]
	v_mfma_f32_16x16x32_bf16 v[58:61], v[168:171], v[208:211], v[58:61]
	v_mfma_f32_16x16x32_bf16 v[46:49], v[156:159], v[216:219], v[46:49]
	v_mfma_f32_16x16x32_bf16 v[42:45], v[168:171], v[216:219], v[42:45]
	v_mfma_f32_16x16x32_bf16 v[30:33], v[156:159], v[224:227], v[30:33]
	v_mfma_f32_16x16x32_bf16 v[26:29], v[168:171], v[224:227], v[26:29]
	v_mfma_f32_16x16x32_bf16 v[14:17], v[156:159], v[232:235], v[14:17]
	v_mfma_f32_16x16x32_bf16 v[10:13], v[168:171], v[232:235], v[10:13]
	s_setprio 0
	s_setprio 1
	v_mfma_f32_16x16x32_bf16 v[62:65], v[164:167], v[212:215], v[62:65]
	v_mfma_f32_16x16x32_bf16 v[58:61], v[172:175], v[212:215], v[58:61]
	v_mfma_f32_16x16x32_bf16 v[46:49], v[164:167], v[220:223], v[46:49]
	v_mfma_f32_16x16x32_bf16 v[42:45], v[172:175], v[220:223], v[42:45]
	v_mfma_f32_16x16x32_bf16 v[30:33], v[164:167], v[228:231], v[30:33]
	v_mfma_f32_16x16x32_bf16 v[26:29], v[172:175], v[228:231], v[26:29]
	v_mfma_f32_16x16x32_bf16 v[14:17], v[164:167], v[236:239], v[14:17]
	v_mfma_f32_16x16x32_bf16 v[10:13], v[172:175], v[236:239], v[10:13]
	s_setprio 0
	s_setprio 1
	v_mfma_f32_16x16x32_bf16 v[54:57], v[176:179], v[208:211], v[54:57]
	v_mfma_f32_16x16x32_bf16 v[50:53], v[184:187], v[208:211], v[50:53]
	v_mfma_f32_16x16x32_bf16 v[38:41], v[176:179], v[216:219], v[38:41]
	v_mfma_f32_16x16x32_bf16 v[34:37], v[184:187], v[216:219], v[34:37]
	v_mfma_f32_16x16x32_bf16 v[22:25], v[176:179], v[224:227], v[22:25]
	v_mfma_f32_16x16x32_bf16 v[18:21], v[184:187], v[224:227], v[18:21]
	v_mfma_f32_16x16x32_bf16 v[6:9], v[176:179], v[232:235], v[6:9]
	v_mfma_f32_16x16x32_bf16 v[2:5], v[184:187], v[232:235], v[2:5]
	s_setprio 0
	s_setprio 1
	v_mfma_f32_16x16x32_bf16 v[54:57], v[180:183], v[212:215], v[54:57]
	v_mfma_f32_16x16x32_bf16 v[50:53], v[204:207], v[212:215], v[50:53]
	v_mfma_f32_16x16x32_bf16 v[38:41], v[180:183], v[220:223], v[38:41]
	v_mfma_f32_16x16x32_bf16 v[34:37], v[204:207], v[220:223], v[34:37]
	s_setprio 0
	v_mfma_f32_16x16x32_bf16 v[22:25], v[180:183], v[228:231], v[22:25]
	v_mfma_f32_16x16x32_bf16 v[18:21], v[204:207], v[228:231], v[18:21]
	v_mfma_f32_16x16x32_bf16 v[6:9], v[180:183], v[236:239], v[6:9]
	v_mfma_f32_16x16x32_bf16 v[2:5], v[204:207], v[236:239], v[2:5]
	s_barrier
	s_add_i32 s67, s67, 2
	s_add_u32 s36, s36, 0x100
	s_addc_u32 s37, s37, 0
	s_add_u32 s62, s62, 0x100
	s_addc_u32 s63, s63, 0
	s_cmp_gt_u32 s67, 29
	s_cbranch_scc0 .LBB0_281
	s_and_b64 vcc, exec, s[4:5]
	s_cbranch_vccnz .LBB0_286
	s_cmp_lt_i32 s57, 30
	s_mov_b64 s[18:19], -1
	s_cbranch_scc1 .LBB0_287
